# adds sample FFN-down epilogue load batching and sample mem-attn Q streaming
# speedup vs baseline: 1.0356x; 1.0104x over previous
; #define PG8_STAGE(bufoff, gbase, voff) do { _Pragma("unroll") for (int _i = 0; _i < 2; ++_i) \
;         __builtin_amdgcn_global_load_lds((const unsigned*)((const char*)(gbase) + (size_t)_i * vst##voff + v##voff), (LAS unsigned*)(lds + (bufoff) + ldsw + _i * 8192), 16, 0, 0); } while (0)
; #define PG8_LDA(dst, b, h) do { _Pragma("unroll") for (int m = 0; m < 4; ++m) _Pragma("unroll") for (int k = 0; k < 2; ++k) dst[m][k] = *(const LAS bf16x8*)(lds + PG8_SA(b, h) + aoff + m * 2048 + k * 1024); } while (0)
; #define PG8_LDB(dst, b, h) do { _Pragma("unroll") for (int n = 0; n < 2; ++n) _Pragma("unroll") for (int k = 0; k < 2; ++k) dst[n][k] = *(const LAS bf16x8*)(lds + PG8_SB(b, h) + boff + n * 2048 + k * 1024); } while (0)
; #define PG8_MMA(ai, bj, At, Bt) do { __builtin_amdgcn_s_setprio(1); _Pragma("unroll") for (int m = 0; m < 4; ++m) _Pragma("unroll") for (int n = 0; n < 2; ++n) _Pragma("unroll") for (int k = 0; k < 2; ++k) \
;         acc[ai][bj][m][n] = __builtin_amdgcn_mfma_f32_16x16x32_bf16(Bt[n][k], At[m][k], acc[ai][bj][m][n], 0, 0, 0); __builtin_amdgcn_s_setprio(0); } while (0)
; #define PG8_WAIT_L(n) asm volatile("s_waitcnt lgkmcnt(" #n ")" ::: "memory")
; #define PG8_BAR __builtin_amdgcn_s_barrier()
; #define PG8_SCHED __builtin_amdgcn_sched_barrier(0)
; template <class Epi>
; DI void gemm_phase(LAS unsigned char* lds, const Gemm g, const StaticOrder& S, const Epi& E, const int tid) {
;     ...
;         for (int t = 0; t < nt; t += 2) {
;             const bool last = (t == nt - 2);
;             const char* a1 = cA + (size_t)(t + 1) * kstep;
;             const char* a2 = last ? nA : cA + (size_t)(t + 2) * kstep; const char* b2 = last ? nB : cB + (size_t)(t + 2) * kstep;
;             const char* a3 = a2 + kstep; const char* b3 = b2 + kstep;
;             PG8_LDB(B0, 0, 0); PG8_SCHED; PG8_LDA(At, 0, 0); PG8_STAGE(PG8_SA(1, 1), a1 + hsA, offA);
;             PG8_WAIT_L(8); PG8_BAR; PG8_WAIT_L(0); PG8_MMA(0, 0, At, B0); PG8_BAR; PG8_SCHED;
;             PG8_LDB(B1, 0, 1); PG8_STAGE(PG8_SB(0, 0), b2, offB);
;             PG8_BAR; PG8_WAIT_L(0); PG8_MMA(0, 1, At, B1); PG8_BAR;
;             PG8_LDA(At, 0, 1); PG8_STAGE(PG8_SA(0, 0), a2, offA);
;             PG8_BAR; PG8_WAIT_L(0); PG8_MMA(1, 0, At, B0); PG8_BAR; PG8_SCHED;
.LBB0_1001:
	s_add_u32 s41, s16, 0xfff50080
	s_addc_u32 s42, s17, -1
	s_add_i32 s58, 0, 0x10000
	v_add_u32_e32 v146, s58, v136
	ds_read_b128 v[132:135], v146
	ds_read_b128 v[138:141], v146 offset:1024
	ds_read_b128 v[142:145], v146 offset:2048
	ds_read_b128 v[146:149], v146 offset:3072
	s_cmp_eq_u32 s40, 18
	s_cselect_b32 s43, s15, s42
	s_cselect_b32 s42, s14, s41
	s_cselect_b32 s47, s9, s19
	s_cselect_b32 s46, s8, s18
	v_lshl_add_u64 v[182:183], s[16:17], 0, v[130:131]
	s_add_i32 m0, s26, 0xc000
	ds_read_b128 v[150:153], v137
	ds_read_b128 v[154:157], v137 offset:1024
	ds_read_b128 v[158:161], v137 offset:2048
	ds_read_b128 v[162:165], v137 offset:3072
	ds_read_b128 v[166:169], v137 offset:4096
	ds_read_b128 v[170:173], v137 offset:5120
	ds_read_b128 v[174:177], v137 offset:6144
	ds_read_b128 v[178:181], v137 offset:7168
	global_load_lds_dwordx4 v[182:183], off
	v_lshl_add_u64 v[182:183], v[182:183], 0, s[92:93]
	s_add_i32 m0, s26, 0xe000
	s_nop 0
	global_load_lds_dwordx4 v[182:183], off
	s_waitcnt lgkmcnt(8)
	s_barrier
	s_waitcnt lgkmcnt(0)
	s_setprio 1
	s_waitcnt lgkmcnt(0)
	v_mfma_f32_16x16x32_bf16 v[126:129], v[132:135], v[150:153], v[126:129]
	v_mfma_f32_16x16x32_bf16 v[122:125], v[142:145], v[150:153], v[122:125]
	v_mfma_f32_16x16x32_bf16 v[114:117], v[132:135], v[158:161], v[114:117]
	v_mfma_f32_16x16x32_bf16 v[106:109], v[142:145], v[158:161], v[106:109]
	v_mfma_f32_16x16x32_bf16 v[98:101], v[132:135], v[166:169], v[98:101]
	v_mfma_f32_16x16x32_bf16 v[90:93], v[142:145], v[166:169], v[90:93]
	v_mfma_f32_16x16x32_bf16 v[82:85], v[132:135], v[174:177], v[82:85]
	v_mfma_f32_16x16x32_bf16 v[74:77], v[142:145], v[174:177], v[74:77]
	v_mfma_f32_16x16x32_bf16 v[126:129], v[138:141], v[154:157], v[126:129]
	v_mfma_f32_16x16x32_bf16 v[122:125], v[146:149], v[154:157], v[122:125]
	v_mfma_f32_16x16x32_bf16 v[114:117], v[138:141], v[162:165], v[114:117]
	v_mfma_f32_16x16x32_bf16 v[106:109], v[146:149], v[162:165], v[106:109]
	v_mfma_f32_16x16x32_bf16 v[98:101], v[138:141], v[170:173], v[98:101]
	v_mfma_f32_16x16x32_bf16 v[90:93], v[146:149], v[170:173], v[90:93]
	v_mfma_f32_16x16x32_bf16 v[82:85], v[138:141], v[178:181], v[82:85]
	v_mfma_f32_16x16x32_bf16 v[74:77], v[146:149], v[178:181], v[74:77]
	s_setprio 0
	s_barrier
	s_add_i32 s41, 0, 0x14000
	v_add_u32_e32 v186, s41, v136
	ds_read_b128 v[182:185], v186
	ds_read_b128 v[200:203], v186 offset:1024
	ds_read_b128 v[204:207], v186 offset:2048
	ds_read_b128 v[208:211], v186 offset:3072
	v_lshl_add_u64 v[186:187], s[46:47], 0, v[0:1]
	s_add_i32 s46, s58, s25
	s_mov_b32 m0, s46
	v_lshl_add_u64 v[188:189], v[186:187], 0, s[92:93]
	global_load_lds_dwordx4 v[186:187], off
	s_add_i32 m0, s46, 0x2000
	s_nop 0
	global_load_lds_dwordx4 v[188:189], off
	s_barrier
	s_waitcnt lgkmcnt(0)
	s_setprio 1
	s_waitcnt lgkmcnt(0)
	v_mfma_f32_16x16x32_bf16 v[118:121], v[182:185], v[150:153], v[118:121]
	v_mfma_f32_16x16x32_bf16 v[110:113], v[204:207], v[150:153], v[110:113]
	v_mfma_f32_16x16x32_bf16 v[102:105], v[182:185], v[158:161], v[102:105]
	v_mfma_f32_16x16x32_bf16 v[94:97], v[204:207], v[158:161], v[94:97]
	v_mfma_f32_16x16x32_bf16 v[86:89], v[182:185], v[166:169], v[86:89]
	v_mfma_f32_16x16x32_bf16 v[78:81], v[204:207], v[166:169], v[78:81]
	v_mfma_f32_16x16x32_bf16 v[70:73], v[182:185], v[174:177], v[70:73]
	v_mfma_f32_16x16x32_bf16 v[66:69], v[204:207], v[174:177], v[66:69]
	v_mfma_f32_16x16x32_bf16 v[118:121], v[200:203], v[154:157], v[118:121]
	v_mfma_f32_16x16x32_bf16 v[110:113], v[208:211], v[154:157], v[110:113]
	v_mfma_f32_16x16x32_bf16 v[102:105], v[200:203], v[162:165], v[102:105]
	v_mfma_f32_16x16x32_bf16 v[94:97], v[208:211], v[162:165], v[94:97]
	v_mfma_f32_16x16x32_bf16 v[86:89], v[200:203], v[170:173], v[86:89]
	v_mfma_f32_16x16x32_bf16 v[78:81], v[208:211], v[170:173], v[78:81]
	v_mfma_f32_16x16x32_bf16 v[70:73], v[200:203], v[178:181], v[70:73]
	v_mfma_f32_16x16x32_bf16 v[66:69], v[208:211], v[178:181], v[66:69]
	s_setprio 0
	s_mov_b32 m0, s26
	v_lshl_add_u64 v[188:189], s[42:43], 0, v[0:1]
	s_barrier
	ds_read_b128 v[150:153], v137 offset:16384
	ds_read_b128 v[154:157], v137 offset:17408
	ds_read_b128 v[158:161], v137 offset:18432
	ds_read_b128 v[162:165], v137 offset:19456
	ds_read_b128 v[166:169], v137 offset:20480
	ds_read_b128 v[170:173], v137 offset:21504
	ds_read_b128 v[174:177], v137 offset:22528
	ds_read_b128 v[178:181], v137 offset:23552
	global_load_lds_dwordx4 v[188:189], off
	v_lshl_add_u64 v[190:191], v[188:189], 0, s[92:93]
	s_mov_b32 m0, s27
	s_nop 0
	global_load_lds_dwordx4 v[190:191], off
	s_barrier
	s_waitcnt lgkmcnt(0)
	s_setprio 1
	s_waitcnt lgkmcnt(0)
	v_mfma_f32_16x16x32_bf16 v[62:65], v[132:135], v[150:153], v[62:65]
	v_mfma_f32_16x16x32_bf16 v[58:61], v[142:145], v[150:153], v[58:61]
	v_mfma_f32_16x16x32_bf16 v[50:53], v[132:135], v[158:161], v[50:53]
	v_mfma_f32_16x16x32_bf16 v[42:45], v[142:145], v[158:161], v[42:45]
	v_mfma_f32_16x16x32_bf16 v[34:37], v[132:135], v[166:169], v[34:37]
	v_mfma_f32_16x16x32_bf16 v[26:29], v[142:145], v[166:169], v[26:29]
	v_mfma_f32_16x16x32_bf16 v[18:21], v[132:135], v[174:177], v[18:21]
	v_mfma_f32_16x16x32_bf16 v[10:13], v[142:145], v[174:177], v[10:13]
	v_mfma_f32_16x16x32_bf16 v[62:65], v[138:141], v[154:157], v[62:65]
	v_mfma_f32_16x16x32_bf16 v[58:61], v[146:149], v[154:157], v[58:61]
	v_mfma_f32_16x16x32_bf16 v[50:53], v[138:141], v[162:165], v[50:53]
	v_mfma_f32_16x16x32_bf16 v[42:45], v[146:149], v[162:165], v[42:45]
	v_mfma_f32_16x16x32_bf16 v[34:37], v[138:141], v[170:173], v[34:37]
	v_mfma_f32_16x16x32_bf16 v[26:29], v[146:149], v[170:173], v[26:29]
	v_mfma_f32_16x16x32_bf16 v[18:21], v[138:141], v[178:181], v[18:21]
	v_mfma_f32_16x16x32_bf16 v[10:13], v[146:149], v[178:181], v[10:13]
	s_setprio 0
	s_barrier
; #define PG8_STAGE(bufoff, gbase, voff) do { _Pragma("unroll") for (int _i = 0; _i < 2; ++_i) \
;         __builtin_amdgcn_global_load_lds((const unsigned*)((const char*)(gbase) + (size_t)_i * vst##voff + v##voff), (LAS unsigned*)(lds + (bufoff) + ldsw + _i * 8192), 16, 0, 0); } while (0)
; #define PG8_LDA(dst, b, h) do { _Pragma("unroll") for (int m = 0; m < 4; ++m) _Pragma("unroll") for (int k = 0; k < 2; ++k) dst[m][k] = *(const LAS bf16x8*)(lds + PG8_SA(b, h) + aoff + m * 2048 + k * 1024); } while (0)
; #define PG8_LDB(dst, b, h) do { _Pragma("unroll") for (int n = 0; n < 2; ++n) _Pragma("unroll") for (int k = 0; k < 2; ++k) dst[n][k] = *(const LAS bf16x8*)(lds + PG8_SB(b, h) + boff + n * 2048 + k * 1024); } while (0)
; #define PG8_MMA(ai, bj, At, Bt) do { __builtin_amdgcn_s_setprio(1); _Pragma("unroll") for (int m = 0; m < 4; ++m) _Pragma("unroll") for (int n = 0; n < 2; ++n) _Pragma("unroll") for (int k = 0; k < 2; ++k) \
;         acc[ai][bj][m][n] = __builtin_amdgcn_mfma_f32_16x16x32_bf16(Bt[n][k], At[m][k], acc[ai][bj][m][n], 0, 0, 0); __builtin_amdgcn_s_setprio(0); } while (0)
; #define PG8_WAIT_V(n) asm volatile("s_waitcnt vmcnt(" #n ")" ::: "memory")
; #define PG8_WAIT_L(n) asm volatile("s_waitcnt lgkmcnt(" #n ")" ::: "memory")
; #define PG8_BAR __builtin_amdgcn_s_barrier()
; #define PG8_SCHED __builtin_amdgcn_sched_barrier(0)
; template <class Epi>
; DI void gemm_phase(LAS unsigned char* lds, const Gemm g, const StaticOrder& S, const Epi& E, const int tid) {
;     ...
;             PG8_STAGE(PG8_SB(0, 1), b2 + hsB, offB);
;             PG8_WAIT_V(6); PG8_BAR; PG8_MMA(1, 1, At, B1); PG8_BAR;
;             PG8_LDB(B0, 1, 0); PG8_SCHED; PG8_LDA(At, 1, 0); PG8_STAGE(PG8_SA(0, 1), a2 + hsA, offA);
;             PG8_WAIT_L(8); PG8_BAR; PG8_WAIT_L(0); PG8_MMA(0, 0, At, B0); PG8_BAR; PG8_SCHED;
;             PG8_LDB(B1, 1, 1); PG8_STAGE(PG8_SB(1, 0), b3, offB);
;             PG8_BAR; PG8_WAIT_L(0); PG8_MMA(0, 1, At, B1); PG8_BAR;
;             PG8_LDA(At, 1, 1); PG8_STAGE(PG8_SA(1, 0), a3, offA);
;             PG8_BAR; PG8_WAIT_L(0); PG8_MMA(1, 0, At, B0); PG8_BAR; PG8_SCHED;
;             PG8_STAGE(PG8_SB(1, 1), b3 + hsB, offB);
	s_add_i32 s41, s41, s25
	v_lshl_add_u64 v[132:133], v[186:187], 0, s[4:5]
	s_mov_b32 m0, s41
	s_nop 0
	global_load_lds_dwordx4 v[132:133], off
	v_lshl_add_u64 v[132:133], v[186:187], 0, s[96:97]
	s_add_i32 m0, s41, 0x2000
	s_nop 0
	global_load_lds_dwordx4 v[132:133], off
	s_waitcnt vmcnt(6)
	s_barrier
	s_setprio 1
	v_mfma_f32_16x16x32_bf16 v[54:57], v[182:185], v[150:153], v[54:57]
	v_mfma_f32_16x16x32_bf16 v[46:49], v[204:207], v[150:153], v[46:49]
	v_mfma_f32_16x16x32_bf16 v[38:41], v[182:185], v[158:161], v[38:41]
	v_mfma_f32_16x16x32_bf16 v[30:33], v[204:207], v[158:161], v[30:33]
	v_mfma_f32_16x16x32_bf16 v[22:25], v[182:185], v[166:169], v[22:25]
	v_mfma_f32_16x16x32_bf16 v[14:17], v[204:207], v[166:169], v[14:17]
	v_mfma_f32_16x16x32_bf16 v[6:9], v[182:185], v[174:177], v[6:9]
	v_mfma_f32_16x16x32_bf16 v[2:5], v[204:207], v[174:177], v[2:5]
	v_mfma_f32_16x16x32_bf16 v[54:57], v[200:203], v[154:157], v[54:57]
	v_mfma_f32_16x16x32_bf16 v[46:49], v[208:211], v[154:157], v[46:49]
	v_mfma_f32_16x16x32_bf16 v[38:41], v[200:203], v[162:165], v[38:41]
	v_mfma_f32_16x16x32_bf16 v[30:33], v[208:211], v[162:165], v[30:33]
	v_mfma_f32_16x16x32_bf16 v[22:25], v[200:203], v[170:173], v[22:25]
	v_mfma_f32_16x16x32_bf16 v[14:17], v[208:211], v[170:173], v[14:17]
	v_mfma_f32_16x16x32_bf16 v[6:9], v[200:203], v[178:181], v[6:9]
	v_mfma_f32_16x16x32_bf16 v[2:5], v[208:211], v[178:181], v[2:5]
	s_setprio 0
	s_add_i32 s41, 0, 0x18000
	v_add_u32_e32 v146, s41, v136
	s_barrier
	ds_read_b128 v[132:135], v146
	ds_read_b128 v[138:141], v146 offset:1024
	ds_read_b128 v[142:145], v146 offset:2048
	ds_read_b128 v[146:149], v146 offset:3072
	s_mov_b32 m0, s28
	v_lshl_add_u64 v[182:183], v[188:189], 0, s[4:5]
	ds_read_b128 v[150:153], v137 offset:32768
	ds_read_b128 v[154:157], v137 offset:33792
	ds_read_b128 v[158:161], v137 offset:34816
	ds_read_b128 v[162:165], v137 offset:35840
	ds_read_b128 v[166:169], v137 offset:36864
	ds_read_b128 v[170:173], v137 offset:37888
	ds_read_b128 v[174:177], v137 offset:38912
	ds_read_b128 v[178:181], v137 offset:39936
	global_load_lds_dwordx4 v[182:183], off
	v_lshl_add_u64 v[182:183], v[188:189], 0, s[96:97]
	s_mov_b32 m0, s29
	s_nop 0
	global_load_lds_dwordx4 v[182:183], off
	s_waitcnt lgkmcnt(8)
	s_barrier
	s_waitcnt lgkmcnt(0)
	s_setprio 1
	s_waitcnt lgkmcnt(0)
	v_mfma_f32_16x16x32_bf16 v[126:129], v[132:135], v[150:153], v[126:129]
	v_mfma_f32_16x16x32_bf16 v[122:125], v[142:145], v[150:153], v[122:125]
	v_mfma_f32_16x16x32_bf16 v[114:117], v[132:135], v[158:161], v[114:117]
	v_mfma_f32_16x16x32_bf16 v[106:109], v[142:145], v[158:161], v[106:109]
	v_mfma_f32_16x16x32_bf16 v[98:101], v[132:135], v[166:169], v[98:101]
	v_mfma_f32_16x16x32_bf16 v[90:93], v[142:145], v[166:169], v[90:93]
	v_mfma_f32_16x16x32_bf16 v[82:85], v[132:135], v[174:177], v[82:85]
	v_mfma_f32_16x16x32_bf16 v[74:77], v[142:145], v[174:177], v[74:77]
	v_mfma_f32_16x16x32_bf16 v[126:129], v[138:141], v[154:157], v[126:129]
	v_mfma_f32_16x16x32_bf16 v[122:125], v[146:149], v[154:157], v[122:125]
	v_mfma_f32_16x16x32_bf16 v[114:117], v[138:141], v[162:165], v[114:117]
	v_mfma_f32_16x16x32_bf16 v[106:109], v[146:149], v[162:165], v[106:109]
	v_mfma_f32_16x16x32_bf16 v[98:101], v[138:141], v[170:173], v[98:101]
	v_mfma_f32_16x16x32_bf16 v[90:93], v[146:149], v[170:173], v[90:93]
	v_mfma_f32_16x16x32_bf16 v[82:85], v[138:141], v[178:181], v[82:85]
	v_mfma_f32_16x16x32_bf16 v[74:77], v[146:149], v[178:181], v[74:77]
	s_setprio 0
	s_barrier
	s_add_i32 s42, 0, 0x1c000
	v_add_u32_e32 v190, s42, v136
	s_add_i32 s41, s41, s25
	ds_read_b128 v[182:185], v190
	ds_read_b128 v[200:203], v190 offset:1024
	ds_read_b128 v[204:207], v190 offset:2048
	ds_read_b128 v[208:211], v190 offset:3072
	v_lshl_add_u64 v[190:191], v[186:187], 0, s[88:89]
	s_mov_b32 m0, s41
	s_nop 0
	global_load_lds_dwordx4 v[190:191], off
	v_lshl_add_u64 v[190:191], v[186:187], 0, s[0:1]
	s_add_i32 m0, s41, 0x2000
	s_nop 0
	global_load_lds_dwordx4 v[190:191], off
	s_barrier
	s_waitcnt lgkmcnt(0)
	s_setprio 1
	s_waitcnt lgkmcnt(0)
	v_mfma_f32_16x16x32_bf16 v[118:121], v[182:185], v[150:153], v[118:121]
	v_mfma_f32_16x16x32_bf16 v[110:113], v[204:207], v[150:153], v[110:113]
	v_mfma_f32_16x16x32_bf16 v[102:105], v[182:185], v[158:161], v[102:105]
	v_mfma_f32_16x16x32_bf16 v[94:97], v[204:207], v[158:161], v[94:97]
	v_mfma_f32_16x16x32_bf16 v[86:89], v[182:185], v[166:169], v[86:89]
	v_mfma_f32_16x16x32_bf16 v[78:81], v[204:207], v[166:169], v[78:81]
	v_mfma_f32_16x16x32_bf16 v[70:73], v[182:185], v[174:177], v[70:73]
	v_mfma_f32_16x16x32_bf16 v[66:69], v[204:207], v[174:177], v[66:69]
	v_mfma_f32_16x16x32_bf16 v[118:121], v[200:203], v[154:157], v[118:121]
	v_mfma_f32_16x16x32_bf16 v[110:113], v[208:211], v[154:157], v[110:113]
	v_mfma_f32_16x16x32_bf16 v[102:105], v[200:203], v[162:165], v[102:105]
	v_mfma_f32_16x16x32_bf16 v[94:97], v[208:211], v[162:165], v[94:97]
	v_mfma_f32_16x16x32_bf16 v[86:89], v[200:203], v[170:173], v[86:89]
	v_mfma_f32_16x16x32_bf16 v[78:81], v[208:211], v[170:173], v[78:81]
	v_mfma_f32_16x16x32_bf16 v[70:73], v[200:203], v[178:181], v[70:73]
	v_mfma_f32_16x16x32_bf16 v[66:69], v[208:211], v[178:181], v[66:69]
	s_setprio 0
	s_mov_b32 m0, s31
	v_lshl_add_u64 v[190:191], v[188:189], 0, s[88:89]
	s_barrier
	ds_read_b128 v[150:153], v137 offset:49152
	ds_read_b128 v[154:157], v137 offset:50176
	ds_read_b128 v[158:161], v137 offset:51200
	ds_read_b128 v[162:165], v137 offset:52224
	ds_read_b128 v[166:169], v137 offset:53248
	ds_read_b128 v[170:173], v137 offset:54272
	ds_read_b128 v[174:177], v137 offset:55296
	ds_read_b128 v[178:181], v137 offset:56320
	global_load_lds_dwordx4 v[190:191], off
	v_lshl_add_u64 v[188:189], v[188:189], 0, s[0:1]
	s_mov_b32 m0, s34
	s_nop 0
	global_load_lds_dwordx4 v[188:189], off
	s_barrier
; DI float bflo(unsigned w) { return __uint_as_float(w << 16); }
; DI float bfhi(unsigned w) { return __uint_as_float(w & 0xffff0000u); }
; DI int lane_id() { int l; asm volatile("v_mbcnt_lo_u32_b32 %0, -1, 0\n\tv_mbcnt_hi_u32_b32 %0, -1, %0" : "=v"(l)); return l; }
; #define PG8_MMA(ai, bj, At, Bt) do { __builtin_amdgcn_s_setprio(1); _Pragma("unroll") for (int m = 0; m < 4; ++m) _Pragma("unroll") for (int n = 0; n < 2; ++n) _Pragma("unroll") for (int k = 0; k < 2; ++k) \
;         acc[ai][bj][m][n] = __builtin_amdgcn_mfma_f32_16x16x32_bf16(Bt[n][k], At[m][k], acc[ai][bj][m][n], 0, 0, 0); __builtin_amdgcn_s_setprio(0); } while (0)
; #define PG8_WAIT_V(n) asm volatile("s_waitcnt vmcnt(" #n ")" ::: "memory")
; #define PG8_BAR __builtin_amdgcn_s_barrier()
; template <class Epi>
; DI void gemm_phase(LAS unsigned char* lds, const Gemm g, const StaticOrder& S, const Epi& E, const int tid) {
;     ...
;             PG8_WAIT_V(6); PG8_BAR; PG8_MMA(1, 1, At, B1); PG8_BAR;
;         }
;         if constexpr (!Epi::AFTER_DRAIN) { const int t2 = lane_id(); E(acc, cur, wr, wc, t2 & 15, t2 >> 4); }
;         if (!has_next) break;
;     DI void operator()(const AccT& acc, const Unit& u, int wr, int wc, int fr, int fq) const {
; #pragma unroll
;         for (int ai = 0; ai < 2; ++ai)
; #pragma unroll
;             for (int m = 0; m < 4; ++m) {
;                 const int row = u.pm * 256 + ai * 128 + wr * 64 + m * 16 + fr; float ss = 0.f;
; #pragma unroll
;                 for (int bj = 0; bj < 2; ++bj)
; #pragma unroll
;                     for (int n = 0; n < 2; ++n) {
;                         const size_t o = (size_t)row * 1024 + u.pn * 256 + bj * 128 + wc * 32 + n * 16 + fq * 4;
;                         f32x4 hv; if (HBsrc) { const u32x2 hw = *(const u32x2*)(HBsrc + o); hv = (f32x4){bflo(hw.x), bfhi(hw.x), bflo(hw.y), bfhi(hw.y)}; } else hv = *(const f32x4*)(H + o);
;                         const f32x4 v = hv + acc[ai][bj][m][n];
;                         *(f32x4*)(H + o) = v; ss += (v[0] * v[0] + v[1] * v[1]) + (v[2] * v[2] + v[3] * v[3]);
;                     }
	s_waitcnt lgkmcnt(0)
	s_setprio 1
	s_waitcnt lgkmcnt(0)
	v_mfma_f32_16x16x32_bf16 v[62:65], v[132:135], v[150:153], v[62:65]
	v_mfma_f32_16x16x32_bf16 v[58:61], v[142:145], v[150:153], v[58:61]
	v_mfma_f32_16x16x32_bf16 v[50:53], v[132:135], v[158:161], v[50:53]
	v_mfma_f32_16x16x32_bf16 v[42:45], v[142:145], v[158:161], v[42:45]
	v_mfma_f32_16x16x32_bf16 v[34:37], v[132:135], v[166:169], v[34:37]
	v_mfma_f32_16x16x32_bf16 v[26:29], v[142:145], v[166:169], v[26:29]
	v_mfma_f32_16x16x32_bf16 v[18:21], v[132:135], v[174:177], v[18:21]
	v_mfma_f32_16x16x32_bf16 v[10:13], v[142:145], v[174:177], v[10:13]
	v_mfma_f32_16x16x32_bf16 v[62:65], v[138:141], v[154:157], v[62:65]
	v_mfma_f32_16x16x32_bf16 v[58:61], v[146:149], v[154:157], v[58:61]
	v_mfma_f32_16x16x32_bf16 v[50:53], v[138:141], v[162:165], v[50:53]
	v_mfma_f32_16x16x32_bf16 v[42:45], v[146:149], v[162:165], v[42:45]
	v_mfma_f32_16x16x32_bf16 v[34:37], v[138:141], v[170:173], v[34:37]
	v_mfma_f32_16x16x32_bf16 v[26:29], v[146:149], v[170:173], v[26:29]
	v_mfma_f32_16x16x32_bf16 v[18:21], v[138:141], v[178:181], v[18:21]
	v_mfma_f32_16x16x32_bf16 v[10:13], v[146:149], v[178:181], v[10:13]
	s_setprio 0
	s_barrier
	s_add_i32 s41, s42, s25
	v_lshl_add_u64 v[132:133], v[186:187], 0, s[54:55]
	s_mov_b32 m0, s41
	s_nop 0
	global_load_lds_dwordx4 v[132:133], off
	v_lshl_add_u64 v[132:133], v[186:187], 0, s[80:81]
	s_add_i32 m0, s41, 0x2000
	s_nop 0
	global_load_lds_dwordx4 v[132:133], off
	s_waitcnt vmcnt(6)
	s_barrier
	s_setprio 1
	v_mfma_f32_16x16x32_bf16 v[54:57], v[182:185], v[150:153], v[54:57]
	v_mfma_f32_16x16x32_bf16 v[46:49], v[204:207], v[150:153], v[46:49]
	v_mfma_f32_16x16x32_bf16 v[38:41], v[182:185], v[158:161], v[38:41]
	v_mfma_f32_16x16x32_bf16 v[30:33], v[204:207], v[158:161], v[30:33]
	v_mfma_f32_16x16x32_bf16 v[22:25], v[182:185], v[166:169], v[22:25]
	v_mfma_f32_16x16x32_bf16 v[14:17], v[204:207], v[166:169], v[14:17]
	v_mfma_f32_16x16x32_bf16 v[6:9], v[182:185], v[174:177], v[6:9]
	v_mfma_f32_16x16x32_bf16 v[2:5], v[204:207], v[174:177], v[2:5]
	v_mfma_f32_16x16x32_bf16 v[54:57], v[200:203], v[154:157], v[54:57]
	v_mfma_f32_16x16x32_bf16 v[46:49], v[208:211], v[154:157], v[46:49]
	v_mfma_f32_16x16x32_bf16 v[38:41], v[200:203], v[162:165], v[38:41]
	v_mfma_f32_16x16x32_bf16 v[30:33], v[208:211], v[162:165], v[30:33]
	v_mfma_f32_16x16x32_bf16 v[22:25], v[200:203], v[170:173], v[22:25]
	v_mfma_f32_16x16x32_bf16 v[14:17], v[208:211], v[170:173], v[14:17]
	v_mfma_f32_16x16x32_bf16 v[6:9], v[200:203], v[178:181], v[6:9]
	v_mfma_f32_16x16x32_bf16 v[2:5], v[208:211], v[178:181], v[2:5]
	s_setprio 0
	s_add_i32 s40, s40, 2
	s_add_u32 s16, s16, 0x100
	s_addc_u32 s17, s17, 0
	s_add_u32 s18, s18, 0x100
	s_addc_u32 s19, s19, 0
	s_cmp_gt_u32 s40, 19
	s_barrier
	s_cbranch_scc0 .LBB0_1001
	s_lshl_b32 s16, s39, 8
	v_mbcnt_lo_u32_b32 v133, -1, 0
	v_mbcnt_hi_u32_b32 v133, -1, v133
	s_add_i32 s16, s16, s30
	v_and_or_b32 v132, v133, 15, s16
	s_lshl_b32 s16, s38, 8
	v_ashrrev_i32_e32 v133, 2, v133
	s_ashr_i32 s17, s16, 31
	v_and_b32_e32 v134, -4, v133
	v_ashrrev_i32_e32 v135, 31, v134
	s_or_b64 s[16:17], s[16:17], s[90:91]
	v_ashrrev_i32_e32 v133, 31, v132
	v_lshl_add_u64 v[134:135], s[16:17], 0, v[134:135]
	v_lshlrev_b64 v[138:139], 10, v[132:133]
	v_lshl_add_u64 v[138:139], v[134:135], 0, v[138:139]
	v_lshl_add_u64 v[140:141], v[138:139], 1, s[10:11]
	global_load_dwordx2 v[150:151], v[140:141], off
	global_load_dwordx2 v[152:153], v[140:141], off offset:32
	global_load_dwordx2 v[154:155], v[140:141], off offset:256
	global_load_dwordx2 v[156:157], v[140:141], off offset:288
	v_lshl_add_u64 v[138:139], v[138:139], 2, s[6:7]
	s_and_b64 vcc, exec, s[12:13]
	s_mov_b32 s38, s36
	s_mov_b32 s39, s37
	s_mov_b64 s[18:19], s[8:9]
	s_mov_b64 s[16:17], s[14:15]
	s_waitcnt vmcnt(3)
	s_nop 0
	v_mov_b32_e32 v142, v150
	v_mov_b32_e32 v143, v151
	v_lshlrev_b32_e32 v144, 16, v142
	v_and_b32_e32 v145, 0xffff0000, v142
	v_lshlrev_b32_e32 v142, 16, v143
	v_and_b32_e32 v143, 0xffff0000, v143
	v_pk_add_f32 v[128:129], v[128:129], v[142:143]
	v_pk_add_f32 v[126:127], v[126:127], v[144:145]
	global_store_dwordx4 v[138:139], v[126:129], off
	s_waitcnt vmcnt(3)
	s_nop 0
	v_mov_b32_e32 v126, v152
	v_mov_b32_e32 v127, v153
	v_lshlrev_b32_e32 v128, 16, v126
	v_and_b32_e32 v129, 0xffff0000, v126
	v_lshlrev_b32_e32 v126, 16, v127
	v_and_b32_e32 v127, 0xffff0000, v127
	v_pk_add_f32 v[124:125], v[124:125], v[126:127]
	v_pk_add_f32 v[122:123], v[122:123], v[128:129]
	global_store_dwordx4 v[138:139], v[122:125], off offset:64
	s_waitcnt vmcnt(3)
	s_nop 0
	v_mov_b32_e32 v122, v154
	v_mov_b32_e32 v123, v155
	v_lshlrev_b32_e32 v124, 16, v122
	v_and_b32_e32 v125, 0xffff0000, v122
	v_lshlrev_b32_e32 v122, 16, v123
	v_and_b32_e32 v123, 0xffff0000, v123
	v_pk_add_f32 v[120:121], v[120:121], v[122:123]
	v_pk_add_f32 v[118:119], v[118:119], v[124:125]
	global_store_dwordx4 v[138:139], v[118:121], off offset:512
	s_waitcnt vmcnt(3)
	s_nop 0
	v_mov_b32_e32 v118, v156
	v_mov_b32_e32 v119, v157
	v_lshlrev_b32_e32 v124, 16, v118
	v_or_b32_e32 v120, 16, v132
	v_ashrrev_i32_e32 v121, 31, v120
	v_lshlrev_b64 v[120:121], 10, v[120:121]
	v_and_b32_e32 v125, 0xffff0000, v118
	v_lshlrev_b32_e32 v118, 16, v119
	v_and_b32_e32 v119, 0xffff0000, v119
	v_lshl_add_u64 v[120:121], v[120:121], 0, v[134:135]
	v_pk_add_f32 v[112:113], v[112:113], v[118:119]
	v_pk_add_f32 v[110:111], v[110:111], v[124:125]
	v_lshl_add_u64 v[122:123], v[120:121], 1, s[10:11]
	global_store_dwordx4 v[138:139], v[110:113], off offset:576
	global_load_dwordx2 v[150:151], v[122:123], off
	global_load_dwordx2 v[152:153], v[122:123], off offset:32
	global_load_dwordx2 v[154:155], v[122:123], off offset:256
	global_load_dwordx2 v[156:157], v[122:123], off offset:288
	v_lshl_add_u64 v[118:119], v[120:121], 2, s[6:7]
	s_waitcnt vmcnt(3)
; DI float bflo(unsigned w) { return __uint_as_float(w << 16); }
; DI float bfhi(unsigned w) { return __uint_as_float(w & 0xffff0000u); }
;     DI void operator()(const AccT& acc, const Unit& u, int wr, int wc, int fr, int fq) const {
;     ...
;         for (int ai = 0; ai < 2; ++ai)
; #pragma unroll
;             for (int m = 0; m < 4; ++m) {
;                 const int row = u.pm * 256 + ai * 128 + wr * 64 + m * 16 + fr; float ss = 0.f;
; #pragma unroll
;                 for (int bj = 0; bj < 2; ++bj)
; #pragma unroll
;                     for (int n = 0; n < 2; ++n) {
;                         const size_t o = (size_t)row * 1024 + u.pn * 256 + bj * 128 + wc * 32 + n * 16 + fq * 4;
;                         f32x4 hv; if (HBsrc) { const u32x2 hw = *(const u32x2*)(HBsrc + o); hv = (f32x4){bflo(hw.x), bfhi(hw.x), bflo(hw.y), bfhi(hw.y)}; } else hv = *(const f32x4*)(H + o);
;                         const f32x4 v = hv + acc[ai][bj][m][n];
;                         *(f32x4*)(H + o) = v; ss += (v[0] * v[0] + v[1] * v[1]) + (v[2] * v[2] + v[3] * v[3]);
;                     }
	s_nop 0
	v_mov_b32_e32 v110, v150
	v_mov_b32_e32 v111, v151
	v_lshlrev_b32_e32 v120, 16, v110
	v_and_b32_e32 v121, 0xffff0000, v110
	v_lshlrev_b32_e32 v110, 16, v111
	v_and_b32_e32 v111, 0xffff0000, v111
	v_pk_add_f32 v[112:113], v[116:117], v[110:111]
	v_pk_add_f32 v[110:111], v[114:115], v[120:121]
	global_store_dwordx4 v[118:119], v[110:113], off
	s_waitcnt vmcnt(3)
	s_nop 0
	v_mov_b32_e32 v110, v152
	v_mov_b32_e32 v111, v153
	v_lshlrev_b32_e32 v112, 16, v110
	v_and_b32_e32 v113, 0xffff0000, v110
	v_lshlrev_b32_e32 v110, 16, v111
	v_and_b32_e32 v111, 0xffff0000, v111
	v_pk_add_f32 v[108:109], v[108:109], v[110:111]
	v_pk_add_f32 v[106:107], v[106:107], v[112:113]
	global_store_dwordx4 v[118:119], v[106:109], off offset:64
	s_waitcnt vmcnt(3)
	s_nop 0
	v_mov_b32_e32 v106, v154
	v_mov_b32_e32 v107, v155
	v_lshlrev_b32_e32 v108, 16, v106
	v_and_b32_e32 v109, 0xffff0000, v106
	v_lshlrev_b32_e32 v106, 16, v107
	v_and_b32_e32 v107, 0xffff0000, v107
	v_pk_add_f32 v[104:105], v[104:105], v[106:107]
	v_pk_add_f32 v[102:103], v[102:103], v[108:109]
	global_store_dwordx4 v[118:119], v[102:105], off offset:512
	s_waitcnt vmcnt(3)
	s_nop 0
	v_mov_b32_e32 v102, v156
	v_mov_b32_e32 v103, v157
	v_lshlrev_b32_e32 v108, 16, v102
	v_or_b32_e32 v104, 32, v132
	v_ashrrev_i32_e32 v105, 31, v104
	v_lshlrev_b64 v[104:105], 10, v[104:105]
	v_and_b32_e32 v109, 0xffff0000, v102
	v_lshlrev_b32_e32 v102, 16, v103
	v_and_b32_e32 v103, 0xffff0000, v103
	v_lshl_add_u64 v[104:105], v[104:105], 0, v[134:135]
	v_pk_add_f32 v[96:97], v[96:97], v[102:103]
	v_pk_add_f32 v[94:95], v[94:95], v[108:109]
	v_lshl_add_u64 v[106:107], v[104:105], 1, s[10:11]
	global_store_dwordx4 v[118:119], v[94:97], off offset:576
	global_load_dwordx2 v[150:151], v[106:107], off
	global_load_dwordx2 v[152:153], v[106:107], off offset:32
	global_load_dwordx2 v[154:155], v[106:107], off offset:256
	global_load_dwordx2 v[156:157], v[106:107], off offset:288
	v_lshl_add_u64 v[102:103], v[104:105], 2, s[6:7]
	s_waitcnt vmcnt(3)
	s_nop 0
	v_mov_b32_e32 v94, v150
	v_mov_b32_e32 v95, v151
	v_lshlrev_b32_e32 v104, 16, v94
	v_and_b32_e32 v105, 0xffff0000, v94
	v_lshlrev_b32_e32 v94, 16, v95
	v_and_b32_e32 v95, 0xffff0000, v95
	v_pk_add_f32 v[96:97], v[100:101], v[94:95]
	v_pk_add_f32 v[94:95], v[98:99], v[104:105]
	global_store_dwordx4 v[102:103], v[94:97], off
	s_waitcnt vmcnt(3)
	s_nop 0
	v_mov_b32_e32 v94, v152
	v_mov_b32_e32 v95, v153
	v_lshlrev_b32_e32 v96, 16, v94
	v_and_b32_e32 v97, 0xffff0000, v94
	v_lshlrev_b32_e32 v94, 16, v95
	v_and_b32_e32 v95, 0xffff0000, v95
	v_pk_add_f32 v[92:93], v[92:93], v[94:95]
	v_pk_add_f32 v[90:91], v[90:91], v[96:97]
	global_store_dwordx4 v[102:103], v[90:93], off offset:64
	s_waitcnt vmcnt(3)
	s_nop 0
	v_mov_b32_e32 v90, v154
	v_mov_b32_e32 v91, v155
	v_lshlrev_b32_e32 v92, 16, v90
	v_and_b32_e32 v93, 0xffff0000, v90
	v_lshlrev_b32_e32 v90, 16, v91
	v_and_b32_e32 v91, 0xffff0000, v91
	v_pk_add_f32 v[88:89], v[88:89], v[90:91]
	v_pk_add_f32 v[86:87], v[86:87], v[92:93]
	global_store_dwordx4 v[102:103], v[86:89], off offset:512
	s_waitcnt vmcnt(3)
	s_nop 0
	v_mov_b32_e32 v86, v156
	v_mov_b32_e32 v87, v157
	v_lshlrev_b32_e32 v92, 16, v86
	v_or_b32_e32 v88, 48, v132
	v_ashrrev_i32_e32 v89, 31, v88
	v_lshlrev_b64 v[88:89], 10, v[88:89]
	v_and_b32_e32 v93, 0xffff0000, v86
	v_lshlrev_b32_e32 v86, 16, v87
	v_and_b32_e32 v87, 0xffff0000, v87
	v_lshl_add_u64 v[88:89], v[88:89], 0, v[134:135]
	v_pk_add_f32 v[80:81], v[80:81], v[86:87]
	v_pk_add_f32 v[78:79], v[78:79], v[92:93]
	v_lshl_add_u64 v[90:91], v[88:89], 1, s[10:11]
	global_store_dwordx4 v[102:103], v[78:81], off offset:576
	global_load_dwordx2 v[150:151], v[90:91], off
	global_load_dwordx2 v[152:153], v[90:91], off offset:32
	global_load_dwordx2 v[154:155], v[90:91], off offset:256
	global_load_dwordx2 v[156:157], v[90:91], off offset:288
	v_lshl_add_u64 v[86:87], v[88:89], 2, s[6:7]
	s_waitcnt vmcnt(3)
	s_nop 0
	v_mov_b32_e32 v78, v150
	v_mov_b32_e32 v79, v151
	v_lshlrev_b32_e32 v88, 16, v78
	v_and_b32_e32 v89, 0xffff0000, v78
	v_lshlrev_b32_e32 v78, 16, v79
	v_and_b32_e32 v79, 0xffff0000, v79
	v_pk_add_f32 v[80:81], v[84:85], v[78:79]
	v_pk_add_f32 v[78:79], v[82:83], v[88:89]
	global_store_dwordx4 v[86:87], v[78:81], off
	s_waitcnt vmcnt(3)
	s_nop 0
	v_mov_b32_e32 v78, v152
	v_mov_b32_e32 v79, v153
	v_lshlrev_b32_e32 v80, 16, v78
	v_and_b32_e32 v81, 0xffff0000, v78
	v_lshlrev_b32_e32 v78, 16, v79
	v_and_b32_e32 v79, 0xffff0000, v79
	v_pk_add_f32 v[76:77], v[76:77], v[78:79]
	v_pk_add_f32 v[74:75], v[74:75], v[80:81]
	global_store_dwordx4 v[86:87], v[74:77], off offset:64
	s_waitcnt vmcnt(3)
	s_nop 0
	v_mov_b32_e32 v74, v154
	v_mov_b32_e32 v75, v155
	v_lshlrev_b32_e32 v76, 16, v74
	v_and_b32_e32 v77, 0xffff0000, v74
	v_lshlrev_b32_e32 v74, 16, v75
	v_and_b32_e32 v75, 0xffff0000, v75
	v_pk_add_f32 v[72:73], v[72:73], v[74:75]
	v_pk_add_f32 v[70:71], v[70:71], v[76:77]
	global_store_dwordx4 v[86:87], v[70:73], off offset:512
	s_waitcnt vmcnt(3)
	s_nop 0
	v_mov_b32_e32 v70, v156
	v_mov_b32_e32 v71, v157
	v_lshlrev_b32_e32 v76, 16, v70
	v_add_u32_e32 v72, 0x80, v132
	v_ashrrev_i32_e32 v73, 31, v72
	v_lshlrev_b64 v[72:73], 10, v[72:73]
	v_and_b32_e32 v77, 0xffff0000, v70
	v_lshlrev_b32_e32 v70, 16, v71
	v_and_b32_e32 v71, 0xffff0000, v71
	v_lshl_add_u64 v[72:73], v[72:73], 0, v[134:135]
	v_pk_add_f32 v[68:69], v[68:69], v[70:71]
	v_pk_add_f32 v[66:67], v[66:67], v[76:77]
	v_lshl_add_u64 v[74:75], v[72:73], 1, s[10:11]
	global_store_dwordx4 v[86:87], v[66:69], off offset:576
	global_load_dwordx2 v[150:151], v[74:75], off
	global_load_dwordx2 v[152:153], v[74:75], off offset:32
	global_load_dwordx2 v[154:155], v[74:75], off offset:256
	global_load_dwordx2 v[156:157], v[74:75], off offset:288
	s_waitcnt vmcnt(3)
; DI float bflo(unsigned w) { return __uint_as_float(w << 16); }
; DI float bfhi(unsigned w) { return __uint_as_float(w & 0xffff0000u); }
;     DI void operator()(const AccT& acc, const Unit& u, int wr, int wc, int fr, int fq) const {
;     ...
;         for (int ai = 0; ai < 2; ++ai)
; #pragma unroll
;             for (int m = 0; m < 4; ++m) {
;                 const int row = u.pm * 256 + ai * 128 + wr * 64 + m * 16 + fr; float ss = 0.f;
; #pragma unroll
;                 for (int bj = 0; bj < 2; ++bj)
; #pragma unroll
;                     for (int n = 0; n < 2; ++n) {
;                         const size_t o = (size_t)row * 1024 + u.pn * 256 + bj * 128 + wc * 32 + n * 16 + fq * 4;
;                         f32x4 hv; if (HBsrc) { const u32x2 hw = *(const u32x2*)(HBsrc + o); hv = (f32x4){bflo(hw.x), bfhi(hw.x), bflo(hw.y), bfhi(hw.y)}; } else hv = *(const f32x4*)(H + o);
;                         const f32x4 v = hv + acc[ai][bj][m][n];
;                         *(f32x4*)(H + o) = v; ss += (v[0] * v[0] + v[1] * v[1]) + (v[2] * v[2] + v[3] * v[3]);
;                     }
	s_nop 0
	v_mov_b32_e32 v66, v150
	v_mov_b32_e32 v67, v151
	v_lshlrev_b32_e32 v70, 16, v66
	v_and_b32_e32 v71, 0xffff0000, v66
	v_lshlrev_b32_e32 v66, 16, v67
	v_and_b32_e32 v67, 0xffff0000, v67
	v_lshl_add_u64 v[68:69], v[72:73], 2, s[6:7]
	v_pk_add_f32 v[64:65], v[64:65], v[66:67]
	v_pk_add_f32 v[62:63], v[62:63], v[70:71]
	global_store_dwordx4 v[68:69], v[62:65], off
	s_waitcnt vmcnt(3)
	s_nop 0
	v_mov_b32_e32 v62, v152
	v_mov_b32_e32 v63, v153
	v_lshlrev_b32_e32 v64, 16, v62
	v_and_b32_e32 v65, 0xffff0000, v62
	v_lshlrev_b32_e32 v62, 16, v63
	v_and_b32_e32 v63, 0xffff0000, v63
	v_pk_add_f32 v[60:61], v[60:61], v[62:63]
	v_pk_add_f32 v[58:59], v[58:59], v[64:65]
	global_store_dwordx4 v[68:69], v[58:61], off offset:64
	s_waitcnt vmcnt(3)
	s_nop 0
	v_mov_b32_e32 v58, v154
	v_mov_b32_e32 v59, v155
	v_lshlrev_b32_e32 v60, 16, v58
	v_and_b32_e32 v61, 0xffff0000, v58
	v_lshlrev_b32_e32 v58, 16, v59
	v_and_b32_e32 v59, 0xffff0000, v59
	v_pk_add_f32 v[56:57], v[56:57], v[58:59]
	v_pk_add_f32 v[54:55], v[54:55], v[60:61]
	global_store_dwordx4 v[68:69], v[54:57], off offset:512
	s_waitcnt vmcnt(3)
	s_nop 0
	v_mov_b32_e32 v54, v156
	v_mov_b32_e32 v55, v157
	v_lshlrev_b32_e32 v60, 16, v54
	v_add_u32_e32 v56, 0x90, v132
	v_ashrrev_i32_e32 v57, 31, v56
	v_lshlrev_b64 v[56:57], 10, v[56:57]
	v_and_b32_e32 v61, 0xffff0000, v54
	v_lshlrev_b32_e32 v54, 16, v55
	v_and_b32_e32 v55, 0xffff0000, v55
	v_lshl_add_u64 v[56:57], v[56:57], 0, v[134:135]
	v_pk_add_f32 v[48:49], v[48:49], v[54:55]
	v_pk_add_f32 v[46:47], v[46:47], v[60:61]
	v_lshl_add_u64 v[58:59], v[56:57], 1, s[10:11]
	global_store_dwordx4 v[68:69], v[46:49], off offset:576
	global_load_dwordx2 v[150:151], v[58:59], off
	global_load_dwordx2 v[152:153], v[58:59], off offset:32
	global_load_dwordx2 v[154:155], v[58:59], off offset:256
	global_load_dwordx2 v[156:157], v[58:59], off offset:288
	v_lshl_add_u64 v[54:55], v[56:57], 2, s[6:7]
	s_waitcnt vmcnt(3)
	s_nop 0
	v_mov_b32_e32 v46, v150
	v_mov_b32_e32 v47, v151
	v_lshlrev_b32_e32 v56, 16, v46
	v_and_b32_e32 v57, 0xffff0000, v46
	v_lshlrev_b32_e32 v46, 16, v47
	v_and_b32_e32 v47, 0xffff0000, v47
	v_pk_add_f32 v[48:49], v[52:53], v[46:47]
	v_pk_add_f32 v[46:47], v[50:51], v[56:57]
	global_store_dwordx4 v[54:55], v[46:49], off
	s_waitcnt vmcnt(3)
	s_nop 0
	v_mov_b32_e32 v46, v152
	v_mov_b32_e32 v47, v153
	v_lshlrev_b32_e32 v48, 16, v46
	v_and_b32_e32 v49, 0xffff0000, v46
	v_lshlrev_b32_e32 v46, 16, v47
	v_and_b32_e32 v47, 0xffff0000, v47
	v_pk_add_f32 v[44:45], v[44:45], v[46:47]
	v_pk_add_f32 v[42:43], v[42:43], v[48:49]
	global_store_dwordx4 v[54:55], v[42:45], off offset:64
	s_waitcnt vmcnt(3)
	s_nop 0
	v_mov_b32_e32 v42, v154
	v_mov_b32_e32 v43, v155
	v_lshlrev_b32_e32 v44, 16, v42
	v_and_b32_e32 v45, 0xffff0000, v42
	v_lshlrev_b32_e32 v42, 16, v43
	v_and_b32_e32 v43, 0xffff0000, v43
	v_pk_add_f32 v[40:41], v[40:41], v[42:43]
	v_pk_add_f32 v[38:39], v[38:39], v[44:45]
	global_store_dwordx4 v[54:55], v[38:41], off offset:512
	s_waitcnt vmcnt(3)
	s_nop 0
	v_mov_b32_e32 v38, v156
	v_mov_b32_e32 v39, v157
	v_lshlrev_b32_e32 v44, 16, v38
	v_add_u32_e32 v40, 0xa0, v132
	v_ashrrev_i32_e32 v41, 31, v40
	v_lshlrev_b64 v[40:41], 10, v[40:41]
	v_and_b32_e32 v45, 0xffff0000, v38
	v_lshlrev_b32_e32 v38, 16, v39
	v_and_b32_e32 v39, 0xffff0000, v39
	v_lshl_add_u64 v[40:41], v[40:41], 0, v[134:135]
	v_pk_add_f32 v[32:33], v[32:33], v[38:39]
	v_pk_add_f32 v[30:31], v[30:31], v[44:45]
	v_lshl_add_u64 v[42:43], v[40:41], 1, s[10:11]
	global_store_dwordx4 v[54:55], v[30:33], off offset:576
	global_load_dwordx2 v[150:151], v[42:43], off
	global_load_dwordx2 v[152:153], v[42:43], off offset:32
	global_load_dwordx2 v[154:155], v[42:43], off offset:256
	global_load_dwordx2 v[156:157], v[42:43], off offset:288
	v_lshl_add_u64 v[38:39], v[40:41], 2, s[6:7]
	s_waitcnt vmcnt(3)
; DI float bflo(unsigned w) { return __uint_as_float(w << 16); }
; DI float bfhi(unsigned w) { return __uint_as_float(w & 0xffff0000u); }
; DI int lane_id() { int l; asm volatile("v_mbcnt_lo_u32_b32 %0, -1, 0\n\tv_mbcnt_hi_u32_b32 %0, -1, %0" : "=v"(l)); return l; }
; #define PG8_WAIT_V(n) asm volatile("s_waitcnt vmcnt(" #n ")" ::: "memory")
; #define PG8_BAR __builtin_amdgcn_s_barrier()
; template <class Epi>
; DI void gemm_phase(LAS unsigned char* lds, const Gemm g, const StaticOrder& S, const Epi& E, const int tid) {
;     ...
;         if constexpr (!Epi::AFTER_DRAIN) { const int t2 = lane_id(); E(acc, cur, wr, wc, t2 & 15, t2 >> 4); }
;         if (!has_next) break;
; #pragma unroll
;         for (int a = 0; a < 2; ++a)
; #pragma unroll
;             for (int b = 0; b < 2; ++b)
; #pragma unroll
;                 for (int m = 0; m < 4; ++m)
; #pragma unroll
;                     for (int n = 0; n < 2; ++n) acc[a][b][m][n] = (f32x4){0.f, 0.f, 0.f, 0.f};
;         cur = nxt; cA = nA; cB = nB; ++ui;
;     }
;     PG8_WAIT_V(0);
;     if (wr == 0) PG8_BAR;
;     DI void operator()(const AccT& acc, const Unit& u, int wr, int wc, int fr, int fq) const {
;     ...
;         for (int ai = 0; ai < 2; ++ai)
; #pragma unroll
;             for (int m = 0; m < 4; ++m) {
;                 const int row = u.pm * 256 + ai * 128 + wr * 64 + m * 16 + fr; float ss = 0.f;
; #pragma unroll
;                 for (int bj = 0; bj < 2; ++bj)
; #pragma unroll
;                     for (int n = 0; n < 2; ++n) {
;                         const size_t o = (size_t)row * 1024 + u.pn * 256 + bj * 128 + wc * 32 + n * 16 + fq * 4;
;                         f32x4 hv; if (HBsrc) { const u32x2 hw = *(const u32x2*)(HBsrc + o); hv = (f32x4){bflo(hw.x), bfhi(hw.x), bflo(hw.y), bfhi(hw.y)}; } else hv = *(const f32x4*)(H + o);
;                         const f32x4 v = hv + acc[ai][bj][m][n];
;                         *(f32x4*)(H + o) = v; ss += (v[0] * v[0] + v[1] * v[1]) + (v[2] * v[2] + v[3] * v[3]);
;                     }
	s_nop 0
	v_mov_b32_e32 v30, v150
	v_mov_b32_e32 v31, v151
	v_lshlrev_b32_e32 v40, 16, v30
	v_and_b32_e32 v41, 0xffff0000, v30
	v_lshlrev_b32_e32 v30, 16, v31
	v_and_b32_e32 v31, 0xffff0000, v31
	v_pk_add_f32 v[32:33], v[36:37], v[30:31]
	v_pk_add_f32 v[30:31], v[34:35], v[40:41]
	global_store_dwordx4 v[38:39], v[30:33], off
	s_waitcnt vmcnt(3)
	s_nop 0
	v_mov_b32_e32 v30, v152
	v_mov_b32_e32 v31, v153
	v_lshlrev_b32_e32 v32, 16, v30
	v_and_b32_e32 v33, 0xffff0000, v30
	v_lshlrev_b32_e32 v30, 16, v31
	v_and_b32_e32 v31, 0xffff0000, v31
	v_pk_add_f32 v[28:29], v[28:29], v[30:31]
	v_pk_add_f32 v[26:27], v[26:27], v[32:33]
	global_store_dwordx4 v[38:39], v[26:29], off offset:64
	s_waitcnt vmcnt(3)
	s_nop 0
	v_mov_b32_e32 v26, v154
	v_mov_b32_e32 v27, v155
	v_lshlrev_b32_e32 v28, 16, v26
	v_and_b32_e32 v29, 0xffff0000, v26
	v_lshlrev_b32_e32 v26, 16, v27
	v_and_b32_e32 v27, 0xffff0000, v27
	v_pk_add_f32 v[24:25], v[24:25], v[26:27]
	v_pk_add_f32 v[22:23], v[22:23], v[28:29]
	global_store_dwordx4 v[38:39], v[22:25], off offset:512
	s_waitcnt vmcnt(3)
	s_nop 0
	v_mov_b32_e32 v22, v156
	v_mov_b32_e32 v23, v157
	v_lshlrev_b32_e32 v28, 16, v22
	v_add_u32_e32 v24, 0xb0, v132
	v_ashrrev_i32_e32 v25, 31, v24
	v_lshlrev_b64 v[24:25], 10, v[24:25]
	v_and_b32_e32 v29, 0xffff0000, v22
	v_lshlrev_b32_e32 v22, 16, v23
	v_and_b32_e32 v23, 0xffff0000, v23
	v_lshl_add_u64 v[24:25], v[24:25], 0, v[134:135]
	v_pk_add_f32 v[16:17], v[16:17], v[22:23]
	v_pk_add_f32 v[14:15], v[14:15], v[28:29]
	v_lshl_add_u64 v[26:27], v[24:25], 1, s[10:11]
	global_store_dwordx4 v[38:39], v[14:17], off offset:576
	global_load_dwordx2 v[150:151], v[26:27], off
	global_load_dwordx2 v[152:153], v[26:27], off offset:32
	global_load_dwordx2 v[154:155], v[26:27], off offset:256
	global_load_dwordx2 v[156:157], v[26:27], off offset:288
	v_lshl_add_u64 v[22:23], v[24:25], 2, s[6:7]
	s_waitcnt vmcnt(3)
	s_nop 0
	v_mov_b32_e32 v14, v150
	v_mov_b32_e32 v15, v151
	v_lshlrev_b32_e32 v24, 16, v14
	v_and_b32_e32 v25, 0xffff0000, v14
	v_lshlrev_b32_e32 v14, 16, v15
	v_and_b32_e32 v15, 0xffff0000, v15
	v_pk_add_f32 v[16:17], v[20:21], v[14:15]
	v_pk_add_f32 v[14:15], v[18:19], v[24:25]
	global_store_dwordx4 v[22:23], v[14:17], off
	s_waitcnt vmcnt(3)
	s_nop 0
	v_mov_b32_e32 v14, v152
	v_mov_b32_e32 v15, v153
	v_lshlrev_b32_e32 v16, 16, v14
	v_and_b32_e32 v17, 0xffff0000, v14
	v_lshlrev_b32_e32 v14, 16, v15
	v_and_b32_e32 v15, 0xffff0000, v15
	v_pk_add_f32 v[12:13], v[12:13], v[14:15]
	v_pk_add_f32 v[10:11], v[10:11], v[16:17]
	global_store_dwordx4 v[22:23], v[10:13], off offset:64
	s_waitcnt vmcnt(3)
	s_nop 0
	v_mov_b32_e32 v10, v154
	v_mov_b32_e32 v11, v155
	v_lshlrev_b32_e32 v12, 16, v10
	v_and_b32_e32 v13, 0xffff0000, v10
	v_lshlrev_b32_e32 v10, 16, v11
	v_and_b32_e32 v11, 0xffff0000, v11
	v_pk_add_f32 v[8:9], v[8:9], v[10:11]
	v_pk_add_f32 v[6:7], v[6:7], v[12:13]
	global_store_dwordx4 v[22:23], v[6:9], off offset:512
	s_waitcnt vmcnt(3)
	s_nop 0
	v_mov_b32_e32 v6, v156
	v_mov_b32_e32 v7, v157
	v_lshlrev_b32_e32 v8, 16, v6
	v_and_b32_e32 v9, 0xffff0000, v6
	v_lshlrev_b32_e32 v6, 16, v7
	v_and_b32_e32 v7, 0xffff0000, v7
	v_pk_add_f32 v[4:5], v[4:5], v[6:7]
	v_pk_add_f32 v[2:3], v[2:3], v[8:9]
	global_store_dwordx4 v[22:23], v[2:5], off offset:576
	s_cbranch_vccz .LBB0_994
	s_waitcnt vmcnt(0)
	s_cmpk_gt_u32 s20, 0xff
	s_cbranch_scc1 .LBB0_1005
	s_barrier

; #define LAS __attribute__((address_space(3)))
; #define ATT_LOADK(t) do { const char* k1_ = (const char*)K1 + (size_t)(t) * 128 * ldk1; const char* k2_ = (const char*)K2 + (size_t)(t) * 8192; \
;     _Pragma("unroll") for (int j = 0; j < KP; ++j) { \
;         if (MLA && j == 2) kreg[j] = *(const u32x4*)(k2_ + ((unsigned)tid << 4)); else kreg[j] = *(const u32x4*)(k1_ + kgo1 + j * 128); } } while (0)
; template <int DQK, bool MLA, bool QREG = true>
; DI void attn_unit(LAS unsigned char* lds, const bf16_t* Q, int ldq, int nqv, const bf16_t* K1, int ldk1, const bf16_t* K2, const bf16_t* VT, int ldv,
;                   int ntiles, int lim, int nkeys, bf16_t* O, int ldo, int tid, int wid, int lane) {
;     ...
;     for (int t = 0; t < ntiles; ++t) {
;         const int buf = t & 1; const bool more = t + 1 < ntiles;
;         const LAS unsigned char* kb = lds + buf * BUF; const LAS unsigned char* vb = kb + KBYTES;
;         f32x16 s0_, s1_;
;         if (more) ATT_LOADK(t + 1);
.LBB0_1552:
	v_lshl_add_u64 v[14:15], s[8:9], 0, v[150:151]
	global_load_dwordx4 v[2:5], v[14:15], off offset:-256
	global_load_dwordx4 v[6:9], v[14:15], off offset:-128
	global_load_dwordx4 v[10:13], v[14:15], off
	global_load_dwordx4 v[112:115], v[14:15], off offset:128
	s_and_b32 s28, s26, 1
	s_mul_i32 s10, s28, 0xc800
	v_cndmask_b32_e64 v0, 0, 1, s[94:95]
	s_add_i32 s27, s10, 0
	v_cmp_ne_u32_e64 s[16:17], 1, v0
	s_andn2_b64 vcc, exec, s[94:95]
	s_cbranch_vccnz .LBB0_1586
; template <int DQK, bool MLA, bool QREG = true>
; DI void attn_unit(LAS unsigned char* lds, const bf16_t* Q, int ldq, int nqv, const bf16_t* K1, int ldk1, const bf16_t* K2, const bf16_t* VT, int ldv,
;                   int ntiles, int lim, int nkeys, bf16_t* O, int ldo, int tid, int wid, int lane) {
;     ...
;       for (int s = 0; s < DQK / 16; ++s) qf[QREG ? s : 0] = qok ? *(const bf16x8*)(qptr + 16 * s) : zero8; }
	v_add_u32_e32 v0, s27, v143
	v_add_u32_e32 v0, v0, v152
	v_mov_b32_e32 v180, 0
	v_mov_b32_e32 v181, 0
	v_mov_b32_e32 v182, 0
	v_mov_b32_e32 v183, 0
	v_mov_b32_e32 v184, 0
	v_mov_b32_e32 v185, 0
	v_mov_b32_e32 v186, 0
	v_mov_b32_e32 v187, 0
	v_mov_b32_e32 v188, 0
	v_mov_b32_e32 v189, 0
	v_mov_b32_e32 v190, 0
	v_mov_b32_e32 v191, 0
	v_mov_b32_e32 v192, 0
	v_mov_b32_e32 v193, 0
	v_mov_b32_e32 v194, 0
	v_mov_b32_e32 v195, 0
	v_mov_b32_e32 v196, 0
	v_mov_b32_e32 v197, 0
	v_mov_b32_e32 v198, 0
	v_mov_b32_e32 v199, 0
	v_mov_b32_e32 v200, 0
	v_mov_b32_e32 v201, 0
	v_mov_b32_e32 v202, 0
	v_mov_b32_e32 v203, 0
	v_mov_b32_e32 v208, 0
	v_mov_b32_e32 v209, 0
	v_mov_b32_e32 v210, 0
	v_mov_b32_e32 v211, 0
	v_mov_b32_e32 v212, 0
	v_mov_b32_e32 v213, 0
	v_mov_b32_e32 v214, 0
	v_mov_b32_e32 v215, 0
	s_and_saveexec_b64 s[10:11], s[12:13]
	global_load_dwordx4 v[180:183], v[146:147], off
	global_load_dwordx4 v[184:187], v[146:147], off offset:32
	global_load_dwordx4 v[188:191], v[146:147], off offset:64
	global_load_dwordx4 v[192:195], v[146:147], off offset:96
	global_load_dwordx4 v[196:199], v[146:147], off offset:128
	global_load_dwordx4 v[200:203], v[146:147], off offset:160
	global_load_dwordx4 v[208:211], v[146:147], off offset:192
	global_load_dwordx4 v[212:215], v[146:147], off offset:224
	s_or_b64 exec, exec, s[10:11]
	ds_read_b128 v[80:83], v0
	ds_read_b128 v[96:99], v0 offset:16896
	ds_read_b128 v[230:233], v0 offset:32
	ds_read_b128 v[234:237], v0 offset:16928
	ds_read_b128 v[238:241], v0 offset:64
	ds_read_b128 v[242:245], v0 offset:16960
	ds_read_b128 v[246:249], v0 offset:96
	ds_read_b128 v[216:219], v0 offset:16992
	s_waitcnt vmcnt(7) lgkmcnt(7)
	v_mfma_f32_32x32x16_bf16 v[80:95], v[80:83], v[180:183], 0
	s_waitcnt lgkmcnt(6)
	v_mfma_f32_32x32x16_bf16 v[96:111], v[96:99], v[180:183], 0
	s_and_saveexec_b64 s[10:11], s[12:13]
	global_load_dwordx4 v[180:183], v[146:147], off offset:256
	s_or_b64 exec, exec, s[10:11]
	s_waitcnt vmcnt(7) lgkmcnt(5)
	v_mfma_f32_32x32x16_bf16 v[80:95], v[230:233], v[184:187], v[80:95]
	ds_read_b128 v[230:233], v0 offset:128
	s_waitcnt lgkmcnt(5)
	v_mfma_f32_32x32x16_bf16 v[96:111], v[234:237], v[184:187], v[96:111]
	ds_read_b128 v[234:237], v0 offset:17024
	s_and_saveexec_b64 s[10:11], s[12:13]
	global_load_dwordx4 v[184:187], v[146:147], off offset:288
	s_or_b64 exec, exec, s[10:11]
	s_waitcnt vmcnt(7) lgkmcnt(5)
	v_mfma_f32_32x32x16_bf16 v[80:95], v[238:241], v[188:191], v[80:95]
	ds_read_b128 v[238:241], v0 offset:160
	s_waitcnt lgkmcnt(5)
	v_mfma_f32_32x32x16_bf16 v[96:111], v[242:245], v[188:191], v[96:111]
	ds_read_b128 v[242:245], v0 offset:17056
	s_and_saveexec_b64 s[10:11], s[12:13]
	global_load_dwordx4 v[188:191], v[146:147], off offset:320
	s_or_b64 exec, exec, s[10:11]
	s_waitcnt vmcnt(7) lgkmcnt(5)
	v_mfma_f32_32x32x16_bf16 v[80:95], v[246:249], v[192:195], v[80:95]
	ds_read_b128 v[246:249], v0 offset:192
	s_waitcnt lgkmcnt(5)
	v_mfma_f32_32x32x16_bf16 v[96:111], v[216:219], v[192:195], v[96:111]
	ds_read_b128 v[216:219], v0 offset:17088
	s_and_saveexec_b64 s[10:11], s[12:13]
	global_load_dwordx4 v[192:195], v[146:147], off offset:352
	s_or_b64 exec, exec, s[10:11]
	s_waitcnt vmcnt(7) lgkmcnt(5)
	v_mfma_f32_32x32x16_bf16 v[80:95], v[230:233], v[196:199], v[80:95]
	ds_read_b128 v[230:233], v0 offset:224
	s_waitcnt lgkmcnt(5)
	v_mfma_f32_32x32x16_bf16 v[96:111], v[234:237], v[196:199], v[96:111]
	ds_read_b128 v[234:237], v0 offset:17120
	s_and_saveexec_b64 s[10:11], s[12:13]
	global_load_dwordx4 v[196:199], v[146:147], off offset:384
	s_or_b64 exec, exec, s[10:11]
	s_waitcnt vmcnt(7) lgkmcnt(5)
	v_mfma_f32_32x32x16_bf16 v[80:95], v[238:241], v[200:203], v[80:95]
	ds_read_b128 v[238:241], v0 offset:256
	s_waitcnt lgkmcnt(5)
	v_mfma_f32_32x32x16_bf16 v[96:111], v[242:245], v[200:203], v[96:111]
	ds_read_b128 v[242:245], v0 offset:17152
	s_and_saveexec_b64 s[10:11], s[12:13]
	global_load_dwordx4 v[200:203], v[146:147], off offset:416
	s_or_b64 exec, exec, s[10:11]
	s_waitcnt vmcnt(7) lgkmcnt(5)
	v_mfma_f32_32x32x16_bf16 v[80:95], v[246:249], v[208:211], v[80:95]
	ds_read_b128 v[246:249], v0 offset:288
	s_waitcnt lgkmcnt(5)
	v_mfma_f32_32x32x16_bf16 v[96:111], v[216:219], v[208:211], v[96:111]
	ds_read_b128 v[216:219], v0 offset:17184
	s_and_saveexec_b64 s[10:11], s[12:13]
	global_load_dwordx4 v[208:211], v[146:147], off offset:448
	s_or_b64 exec, exec, s[10:11]
	s_waitcnt vmcnt(7) lgkmcnt(5)
	v_mfma_f32_32x32x16_bf16 v[80:95], v[230:233], v[212:215], v[80:95]
	ds_read_b128 v[230:233], v0 offset:320
	s_waitcnt lgkmcnt(5)
	v_mfma_f32_32x32x16_bf16 v[96:111], v[234:237], v[212:215], v[96:111]
	ds_read_b128 v[234:237], v0 offset:17216
	s_and_saveexec_b64 s[10:11], s[12:13]
	global_load_dwordx4 v[212:215], v[146:147], off offset:480
	s_or_b64 exec, exec, s[10:11]
	s_waitcnt vmcnt(7) lgkmcnt(5)
	v_mfma_f32_32x32x16_bf16 v[80:95], v[238:241], v[180:183], v[80:95]
	ds_read_b128 v[238:241], v0 offset:352
	s_waitcnt lgkmcnt(5)
	v_mfma_f32_32x32x16_bf16 v[96:111], v[242:245], v[180:183], v[96:111]
	ds_read_b128 v[242:245], v0 offset:17248
	s_waitcnt vmcnt(6) lgkmcnt(5)
	v_mfma_f32_32x32x16_bf16 v[80:95], v[246:249], v[184:187], v[80:95]
	ds_read_b128 v[246:249], v0 offset:384
	s_waitcnt lgkmcnt(5)
	v_mfma_f32_32x32x16_bf16 v[96:111], v[216:219], v[184:187], v[96:111]
	ds_read_b128 v[216:219], v0 offset:17280
	s_waitcnt vmcnt(5) lgkmcnt(5)
	v_mfma_f32_32x32x16_bf16 v[80:95], v[230:233], v[188:191], v[80:95]
	ds_read_b128 v[230:233], v0 offset:416
	s_waitcnt lgkmcnt(5)
	v_mfma_f32_32x32x16_bf16 v[96:111], v[234:237], v[188:191], v[96:111]
	ds_read_b128 v[234:237], v0 offset:17312
	s_waitcnt vmcnt(4) lgkmcnt(5)
	v_mfma_f32_32x32x16_bf16 v[80:95], v[238:241], v[192:195], v[80:95]
	ds_read_b128 v[238:241], v0 offset:448
	s_waitcnt lgkmcnt(5)
	v_mfma_f32_32x32x16_bf16 v[96:111], v[242:245], v[192:195], v[96:111]
	ds_read_b128 v[242:245], v0 offset:17344
	s_waitcnt vmcnt(3) lgkmcnt(5)
	v_mfma_f32_32x32x16_bf16 v[80:95], v[246:249], v[196:199], v[80:95]
	ds_read_b128 v[246:249], v0 offset:480
	s_waitcnt lgkmcnt(5)
	v_mfma_f32_32x32x16_bf16 v[96:111], v[216:219], v[196:199], v[96:111]
	ds_read_b128 v[216:219], v0 offset:17376
	s_waitcnt vmcnt(2) lgkmcnt(5)
	v_mfma_f32_32x32x16_bf16 v[80:95], v[230:233], v[200:203], v[80:95]
	s_waitcnt lgkmcnt(4)
	v_mfma_f32_32x32x16_bf16 v[96:111], v[234:237], v[200:203], v[96:111]
	s_waitcnt vmcnt(1) lgkmcnt(3)
	v_mfma_f32_32x32x16_bf16 v[80:95], v[238:241], v[208:211], v[80:95]
	s_waitcnt lgkmcnt(2)
	v_mfma_f32_32x32x16_bf16 v[96:111], v[242:245], v[208:211], v[96:111]
	s_waitcnt vmcnt(0) lgkmcnt(1)
	v_mfma_f32_32x32x16_bf16 v[80:95], v[246:249], v[212:215], v[80:95]
	s_waitcnt lgkmcnt(0)
	v_mfma_f32_32x32x16_bf16 v[96:111], v[216:219], v[212:215], v[96:111]

; template <int DQK, bool MLA, bool QREG = true>
; DI void attn_unit(LAS unsigned char* lds, const bf16_t* Q, int ldq, int nqv, const bf16_t* K1, int ldk1, const bf16_t* K2, const bf16_t* VT, int ldv,
;                   int ntiles, int lim, int nkeys, bf16_t* O, int ldo, int tid, int wid, int lane) {
;     ...
;       for (int s = 0; s < DQK / 16; ++s) qf[QREG ? s : 0] = qok ? *(const bf16x8*)(qptr + 16 * s) : zero8; }
.LBB0_1591:
	s_andn2_b64 vcc, exec, s[10:11]
	s_cbranch_vccnz .LBB0_1627
	v_add_u32_e32 v0, v153, v152
	v_mov_b32_e32 v180, 0
	v_mov_b32_e32 v181, 0
	v_mov_b32_e32 v182, 0
	v_mov_b32_e32 v183, 0
	v_mov_b32_e32 v184, 0
	v_mov_b32_e32 v185, 0
	v_mov_b32_e32 v186, 0
	v_mov_b32_e32 v187, 0
	v_mov_b32_e32 v188, 0
	v_mov_b32_e32 v189, 0
	v_mov_b32_e32 v190, 0
	v_mov_b32_e32 v191, 0
	v_mov_b32_e32 v192, 0
	v_mov_b32_e32 v193, 0
	v_mov_b32_e32 v194, 0
	v_mov_b32_e32 v195, 0
	v_mov_b32_e32 v196, 0
	v_mov_b32_e32 v197, 0
	v_mov_b32_e32 v198, 0
	v_mov_b32_e32 v199, 0
	v_mov_b32_e32 v200, 0
	v_mov_b32_e32 v201, 0
	v_mov_b32_e32 v202, 0
	v_mov_b32_e32 v203, 0
	v_mov_b32_e32 v208, 0
	v_mov_b32_e32 v209, 0
	v_mov_b32_e32 v210, 0
	v_mov_b32_e32 v211, 0
	v_mov_b32_e32 v212, 0
	v_mov_b32_e32 v213, 0
	v_mov_b32_e32 v214, 0
	v_mov_b32_e32 v215, 0
	s_and_saveexec_b64 s[10:11], s[12:13]
	global_load_dwordx4 v[180:183], v[146:147], off
	global_load_dwordx4 v[184:187], v[146:147], off offset:32
	global_load_dwordx4 v[188:191], v[146:147], off offset:64
	global_load_dwordx4 v[192:195], v[146:147], off offset:96
	global_load_dwordx4 v[196:199], v[146:147], off offset:128
	global_load_dwordx4 v[200:203], v[146:147], off offset:160
	global_load_dwordx4 v[208:211], v[146:147], off offset:192
	global_load_dwordx4 v[212:215], v[146:147], off offset:224
	s_or_b64 exec, exec, s[10:11]
	ds_read_b128 v[96:99], v0 offset:51200
	ds_read_b128 v[80:83], v155 offset:16896
	ds_read_b128 v[230:233], v0 offset:51232
	ds_read_b128 v[234:237], v155 offset:16928
	ds_read_b128 v[238:241], v0 offset:51264
	ds_read_b128 v[242:245], v155 offset:16960
	ds_read_b128 v[246:249], v0 offset:51296
	ds_read_b128 v[216:219], v155 offset:16992
	s_waitcnt vmcnt(7) lgkmcnt(7)
	v_mfma_f32_32x32x16_bf16 v[96:111], v[96:99], v[180:183], 0
	s_waitcnt lgkmcnt(6)
	v_mfma_f32_32x32x16_bf16 v[80:95], v[80:83], v[180:183], 0
	s_and_saveexec_b64 s[10:11], s[12:13]
	global_load_dwordx4 v[180:183], v[146:147], off offset:256
	s_or_b64 exec, exec, s[10:11]
	s_waitcnt vmcnt(7) lgkmcnt(5)
	v_mfma_f32_32x32x16_bf16 v[96:111], v[230:233], v[184:187], v[96:111]
	ds_read_b128 v[230:233], v0 offset:51328
	s_waitcnt lgkmcnt(5)
	v_mfma_f32_32x32x16_bf16 v[80:95], v[234:237], v[184:187], v[80:95]
	ds_read_b128 v[234:237], v155 offset:17024
	s_and_saveexec_b64 s[10:11], s[12:13]
	global_load_dwordx4 v[184:187], v[146:147], off offset:288
	s_or_b64 exec, exec, s[10:11]
	s_waitcnt vmcnt(7) lgkmcnt(5)
	v_mfma_f32_32x32x16_bf16 v[96:111], v[238:241], v[188:191], v[96:111]
	ds_read_b128 v[238:241], v0 offset:51360
	s_waitcnt lgkmcnt(5)
	v_mfma_f32_32x32x16_bf16 v[80:95], v[242:245], v[188:191], v[80:95]
	ds_read_b128 v[242:245], v155 offset:17056
	s_and_saveexec_b64 s[10:11], s[12:13]
	global_load_dwordx4 v[188:191], v[146:147], off offset:320
	s_or_b64 exec, exec, s[10:11]
	s_waitcnt vmcnt(7) lgkmcnt(5)
	v_mfma_f32_32x32x16_bf16 v[96:111], v[246:249], v[192:195], v[96:111]
	ds_read_b128 v[246:249], v0 offset:51392
	s_waitcnt lgkmcnt(5)
	v_mfma_f32_32x32x16_bf16 v[80:95], v[216:219], v[192:195], v[80:95]
	ds_read_b128 v[216:219], v155 offset:17088
	s_and_saveexec_b64 s[10:11], s[12:13]
	global_load_dwordx4 v[192:195], v[146:147], off offset:352
	s_or_b64 exec, exec, s[10:11]
	s_waitcnt vmcnt(7) lgkmcnt(5)
	v_mfma_f32_32x32x16_bf16 v[96:111], v[230:233], v[196:199], v[96:111]
	ds_read_b128 v[230:233], v0 offset:51424
	s_waitcnt lgkmcnt(5)
	v_mfma_f32_32x32x16_bf16 v[80:95], v[234:237], v[196:199], v[80:95]
	ds_read_b128 v[234:237], v155 offset:17120
	s_and_saveexec_b64 s[10:11], s[12:13]
	global_load_dwordx4 v[196:199], v[146:147], off offset:384
	s_or_b64 exec, exec, s[10:11]
	s_waitcnt vmcnt(7) lgkmcnt(5)
	v_mfma_f32_32x32x16_bf16 v[96:111], v[238:241], v[200:203], v[96:111]
	ds_read_b128 v[238:241], v0 offset:51456
	s_waitcnt lgkmcnt(5)
	v_mfma_f32_32x32x16_bf16 v[80:95], v[242:245], v[200:203], v[80:95]
	ds_read_b128 v[242:245], v155 offset:17152
	s_and_saveexec_b64 s[10:11], s[12:13]
	global_load_dwordx4 v[200:203], v[146:147], off offset:416
	s_or_b64 exec, exec, s[10:11]
	s_waitcnt vmcnt(7) lgkmcnt(5)
	v_mfma_f32_32x32x16_bf16 v[96:111], v[246:249], v[208:211], v[96:111]
	ds_read_b128 v[246:249], v0 offset:51488
	s_waitcnt lgkmcnt(5)
	v_mfma_f32_32x32x16_bf16 v[80:95], v[216:219], v[208:211], v[80:95]
	ds_read_b128 v[216:219], v155 offset:17184
	s_and_saveexec_b64 s[10:11], s[12:13]
	global_load_dwordx4 v[208:211], v[146:147], off offset:448
	s_or_b64 exec, exec, s[10:11]
	s_waitcnt vmcnt(7) lgkmcnt(5)
	v_mfma_f32_32x32x16_bf16 v[96:111], v[230:233], v[212:215], v[96:111]
	ds_read_b128 v[230:233], v0 offset:51520
	s_waitcnt lgkmcnt(5)
	v_mfma_f32_32x32x16_bf16 v[80:95], v[234:237], v[212:215], v[80:95]
	ds_read_b128 v[234:237], v155 offset:17216
	s_and_saveexec_b64 s[10:11], s[12:13]
	global_load_dwordx4 v[212:215], v[146:147], off offset:480
	s_or_b64 exec, exec, s[10:11]
	s_waitcnt vmcnt(7) lgkmcnt(5)
	v_mfma_f32_32x32x16_bf16 v[96:111], v[238:241], v[180:183], v[96:111]
	ds_read_b128 v[238:241], v0 offset:51552
	s_waitcnt lgkmcnt(5)
	v_mfma_f32_32x32x16_bf16 v[80:95], v[242:245], v[180:183], v[80:95]
	ds_read_b128 v[242:245], v155 offset:17248
	s_waitcnt vmcnt(6) lgkmcnt(5)
	v_mfma_f32_32x32x16_bf16 v[96:111], v[246:249], v[184:187], v[96:111]
	ds_read_b128 v[246:249], v0 offset:51584
	s_waitcnt lgkmcnt(5)
	v_mfma_f32_32x32x16_bf16 v[80:95], v[216:219], v[184:187], v[80:95]
	ds_read_b128 v[216:219], v155 offset:17280
	s_waitcnt vmcnt(5) lgkmcnt(5)
	v_mfma_f32_32x32x16_bf16 v[96:111], v[230:233], v[188:191], v[96:111]
	ds_read_b128 v[230:233], v0 offset:51616
	s_waitcnt lgkmcnt(5)
	v_mfma_f32_32x32x16_bf16 v[80:95], v[234:237], v[188:191], v[80:95]
	ds_read_b128 v[234:237], v155 offset:17312
	s_waitcnt vmcnt(4) lgkmcnt(5)
	v_mfma_f32_32x32x16_bf16 v[96:111], v[238:241], v[192:195], v[96:111]
	ds_read_b128 v[238:241], v0 offset:51648
	s_waitcnt lgkmcnt(5)
	v_mfma_f32_32x32x16_bf16 v[80:95], v[242:245], v[192:195], v[80:95]
	ds_read_b128 v[242:245], v155 offset:17344
	s_waitcnt vmcnt(3) lgkmcnt(5)
	v_mfma_f32_32x32x16_bf16 v[96:111], v[246:249], v[196:199], v[96:111]
	ds_read_b128 v[246:249], v0 offset:51680
	s_waitcnt lgkmcnt(5)
	v_mfma_f32_32x32x16_bf16 v[80:95], v[216:219], v[196:199], v[80:95]
	ds_read_b128 v[216:219], v155 offset:17376
	s_waitcnt vmcnt(2) lgkmcnt(5)
	v_mfma_f32_32x32x16_bf16 v[96:111], v[230:233], v[200:203], v[96:111]
	s_waitcnt lgkmcnt(4)
	v_mfma_f32_32x32x16_bf16 v[80:95], v[234:237], v[200:203], v[80:95]
	s_waitcnt vmcnt(1) lgkmcnt(3)
	v_mfma_f32_32x32x16_bf16 v[96:111], v[238:241], v[208:211], v[96:111]
	s_waitcnt lgkmcnt(2)
	v_mfma_f32_32x32x16_bf16 v[80:95], v[242:245], v[208:211], v[80:95]
	s_waitcnt vmcnt(0) lgkmcnt(1)
	v_mfma_f32_32x32x16_bf16 v[96:111], v[246:249], v[212:215], v[96:111]
	s_waitcnt lgkmcnt(0)
	v_mfma_f32_32x32x16_bf16 v[80:95], v[216:219], v[212:215], v[80:95]
	s_nop 15
	v_max3_f32 v0, v96, v97, v98
	v_max3_f32 v0, v0, v99, v100
	v_max3_f32 v0, v0, v101, v102
	v_max3_f32 v0, v0, v103, v104
	v_max3_f32 v0, v0, v105, v106
	v_max3_f32 v0, v0, v107, v108
	v_max3_f32 v0, v0, v109, v110
	v_max_f32 v0, v0, v111
	s_nop 0
	v_max_f32_e32 v0, v0, v0
	s_nop 15
	v_max3_f32 v2, v80, v81, v82
	v_max3_f32 v2, v2, v83, v84
	v_max3_f32 v2, v2, v85, v86
	v_max3_f32 v2, v2, v87, v88
	v_max3_f32 v2, v2, v89, v90
	v_max3_f32 v2, v2, v91, v92
	v_max3_f32 v2, v2, v93, v94
	v_max_f32 v2, v2, v95
	v_xor_b32_e32 v4, 32, v226
	v_max_f32_e32 v2, v2, v2
	v_max_f32_e32 v0, v0, v2
	v_and_b32_e32 v2, 64, v226
	v_add_u32_e32 v5, 64, v2
	v_cmp_lt_i32_e32 vcc, v4, v5
	s_nop 1
	v_cndmask_b32_e32 v2, v226, v4, vcc
	v_lshlrev_b32_e32 v2, 2, v2
	ds_bpermute_b32 v2, v2, v0
	s_waitcnt lgkmcnt(0)
	v_max_f32_e32 v2, v2, v2
	v_max_f32_e32 v0, v0, v2
	v_add_f32_e32 v2, 0x41000000, v157
	v_cmp_gt_f32_e32 vcc, v0, v2
	s_cbranch_vccz .LBB0_1626
	s_nop 0
	v_cndmask_b32_e32 v2, v157, v0, vcc
	v_sub_f32_e32 v0, v157, v2
	v_exp_f32_e32 v0, v0
	v_mov_b32_e32 v157, v2
	v_pk_mul_f32 v[78:79], v[78:79], v[0:1] op_sel_hi:[1,0]
	v_pk_mul_f32 v[76:77], v[76:77], v[0:1] op_sel_hi:[1,0]
	v_pk_mul_f32 v[74:75], v[74:75], v[0:1] op_sel_hi:[1,0]
	v_pk_mul_f32 v[72:73], v[72:73], v[0:1] op_sel_hi:[1,0]
	v_pk_mul_f32 v[70:71], v[70:71], v[0:1] op_sel_hi:[1,0]
	v_pk_mul_f32 v[68:69], v[68:69], v[0:1] op_sel_hi:[1,0]
	v_pk_mul_f32 v[66:67], v[66:67], v[0:1] op_sel_hi:[1,0]
	v_pk_mul_f32 v[64:65], v[64:65], v[0:1] op_sel_hi:[1,0]
	v_pk_mul_f32 v[62:63], v[62:63], v[0:1] op_sel_hi:[1,0]
	v_pk_mul_f32 v[60:61], v[60:61], v[0:1] op_sel_hi:[1,0]
	v_pk_mul_f32 v[58:59], v[58:59], v[0:1] op_sel_hi:[1,0]
	v_pk_mul_f32 v[56:57], v[56:57], v[0:1] op_sel_hi:[1,0]
	v_pk_mul_f32 v[54:55], v[54:55], v[0:1] op_sel_hi:[1,0]
	v_pk_mul_f32 v[52:53], v[52:53], v[0:1] op_sel_hi:[1,0]
	v_pk_mul_f32 v[50:51], v[50:51], v[0:1] op_sel_hi:[1,0]
	v_pk_mul_f32 v[48:49], v[48:49], v[0:1] op_sel_hi:[1,0]
	v_pk_mul_f32 v[46:47], v[46:47], v[0:1] op_sel_hi:[1,0]
	v_pk_mul_f32 v[44:45], v[44:45], v[0:1] op_sel_hi:[1,0]
	v_pk_mul_f32 v[42:43], v[42:43], v[0:1] op_sel_hi:[1,0]
	v_pk_mul_f32 v[40:41], v[40:41], v[0:1] op_sel_hi:[1,0]
	v_pk_mul_f32 v[38:39], v[38:39], v[0:1] op_sel_hi:[1,0]
	v_pk_mul_f32 v[36:37], v[36:37], v[0:1] op_sel_hi:[1,0]
	v_pk_mul_f32 v[34:35], v[34:35], v[0:1] op_sel_hi:[1,0]
	v_pk_mul_f32 v[32:33], v[32:33], v[0:1] op_sel_hi:[1,0]
	v_pk_mul_f32 v[30:31], v[30:31], v[0:1] op_sel_hi:[1,0]
	v_pk_mul_f32 v[28:29], v[28:29], v[0:1] op_sel_hi:[1,0]
	v_pk_mul_f32 v[26:27], v[26:27], v[0:1] op_sel_hi:[1,0]
	v_pk_mul_f32 v[24:25], v[24:25], v[0:1] op_sel_hi:[1,0]
	v_pk_mul_f32 v[22:23], v[22:23], v[0:1] op_sel_hi:[1,0]
	v_pk_mul_f32 v[20:21], v[20:21], v[0:1] op_sel_hi:[1,0]
	v_pk_mul_f32 v[18:19], v[18:19], v[0:1] op_sel_hi:[1,0]
	v_pk_mul_f32 v[16:17], v[16:17], v[0:1] op_sel_hi:[1,0]
	v_mul_f32_e32 v156, v156, v0

; #define PG8_STAGE(bufoff, gbase, voff) do { _Pragma("unroll") for (int _i = 0; _i < 2; ++_i) \
;         __builtin_amdgcn_global_load_lds((const unsigned*)((const char*)(gbase) + (size_t)_i * vst##voff + v##voff), (LAS unsigned*)(lds + (bufoff) + ldsw + _i * 8192), 16, 0, 0); } while (0)
; #define PG8_LDA(dst, b, h) do { _Pragma("unroll") for (int m = 0; m < 4; ++m) _Pragma("unroll") for (int k = 0; k < 2; ++k) dst[m][k] = *(const LAS bf16x8*)(lds + PG8_SA(b, h) + aoff + m * 2048 + k * 1024); } while (0)
; #define PG8_LDB(dst, b, h) do { _Pragma("unroll") for (int n = 0; n < 2; ++n) _Pragma("unroll") for (int k = 0; k < 2; ++k) dst[n][k] = *(const LAS bf16x8*)(lds + PG8_SB(b, h) + boff + n * 2048 + k * 1024); } while (0)
; #define PG8_MMA(ai, bj, At, Bt) do { __builtin_amdgcn_s_setprio(1); _Pragma("unroll") for (int m = 0; m < 4; ++m) _Pragma("unroll") for (int n = 0; n < 2; ++n) _Pragma("unroll") for (int k = 0; k < 2; ++k) \
;         acc[ai][bj][m][n] = __builtin_amdgcn_mfma_f32_16x16x32_bf16(Bt[n][k], At[m][k], acc[ai][bj][m][n], 0, 0, 0); __builtin_amdgcn_s_setprio(0); } while (0)
; #define PG8_WAIT_V(n) asm volatile("s_waitcnt vmcnt(" #n ")" ::: "memory")
; #define PG8_WAIT_L(n) asm volatile("s_waitcnt lgkmcnt(" #n ")" ::: "memory")
; #define PG8_BAR __builtin_amdgcn_s_barrier()
; #define PG8_SCHED __builtin_amdgcn_sched_barrier(0)
; template <class Epi>
; DI void gemm_phase(LAS unsigned char* lds, const Gemm g, const StaticOrder& S, const Epi& E, const int tid) {
;     ...
;             PG8_LDB(B0, 0, 0); PG8_SCHED; PG8_LDA(At, 0, 0); PG8_STAGE(PG8_SA(1, 1), a1 + hsA, offA);
;             PG8_WAIT_L(8); PG8_BAR; PG8_WAIT_L(0); PG8_MMA(0, 0, At, B0); PG8_BAR; PG8_SCHED;
;             PG8_LDB(B1, 0, 1); PG8_STAGE(PG8_SB(0, 0), b2, offB);
;             PG8_BAR; PG8_WAIT_L(0); PG8_MMA(0, 1, At, B1); PG8_BAR;
;             PG8_LDA(At, 0, 1); PG8_STAGE(PG8_SA(0, 0), a2, offA);
;             PG8_BAR; PG8_WAIT_L(0); PG8_MMA(1, 0, At, B0); PG8_BAR; PG8_SCHED;
;             PG8_STAGE(PG8_SB(0, 1), b2 + hsB, offB);
;             PG8_WAIT_V(6); PG8_BAR; PG8_MMA(1, 1, At, B1); PG8_BAR;
.LBB0_1863:
	s_add_u32 s25, s6, 0xfff50080
	s_addc_u32 s46, s7, -1
	s_add_i32 s62, 0, 0x10000
	v_add_u32_e32 v146, s62, v136
	ds_read_b128 v[132:135], v146
	ds_read_b128 v[138:141], v146 offset:1024
	ds_read_b128 v[142:145], v146 offset:2048
	ds_read_b128 v[146:149], v146 offset:3072
	s_cmp_eq_u32 s24, 18
	s_cselect_b32 s47, s15, s46
	s_cselect_b32 s46, s14, s25
	s_cselect_b32 s59, s17, s23
	s_cselect_b32 s58, s16, s22
	v_lshl_add_u64 v[182:183], s[6:7], 0, v[130:131]
	s_add_i32 m0, s30, 0xc000
	ds_read_b128 v[150:153], v137
	ds_read_b128 v[154:157], v137 offset:1024
	ds_read_b128 v[158:161], v137 offset:2048
	ds_read_b128 v[162:165], v137 offset:3072
	ds_read_b128 v[166:169], v137 offset:4096
	ds_read_b128 v[170:173], v137 offset:5120
	ds_read_b128 v[174:177], v137 offset:6144
	ds_read_b128 v[178:181], v137 offset:7168
	global_load_lds_dwordx4 v[182:183], off
	v_lshl_add_u64 v[182:183], v[182:183], 0, s[92:93]
	s_add_i32 m0, s30, 0xe000
	s_nop 0
	global_load_lds_dwordx4 v[182:183], off
	s_waitcnt lgkmcnt(8)
	s_barrier
	s_waitcnt lgkmcnt(0)
	s_setprio 1
	s_waitcnt lgkmcnt(0)
	v_mfma_f32_16x16x32_bf16 v[126:129], v[132:135], v[150:153], v[126:129]
	v_mfma_f32_16x16x32_bf16 v[122:125], v[142:145], v[150:153], v[122:125]
	v_mfma_f32_16x16x32_bf16 v[110:113], v[132:135], v[158:161], v[110:113]
	v_mfma_f32_16x16x32_bf16 v[106:109], v[142:145], v[158:161], v[106:109]
	v_mfma_f32_16x16x32_bf16 v[94:97], v[132:135], v[166:169], v[94:97]
	v_mfma_f32_16x16x32_bf16 v[90:93], v[142:145], v[166:169], v[90:93]
	v_mfma_f32_16x16x32_bf16 v[78:81], v[132:135], v[174:177], v[78:81]
	v_mfma_f32_16x16x32_bf16 v[74:77], v[142:145], v[174:177], v[74:77]
	v_mfma_f32_16x16x32_bf16 v[126:129], v[138:141], v[154:157], v[126:129]
	v_mfma_f32_16x16x32_bf16 v[122:125], v[146:149], v[154:157], v[122:125]
	v_mfma_f32_16x16x32_bf16 v[110:113], v[138:141], v[162:165], v[110:113]
	v_mfma_f32_16x16x32_bf16 v[106:109], v[146:149], v[162:165], v[106:109]
	v_mfma_f32_16x16x32_bf16 v[94:97], v[138:141], v[170:173], v[94:97]
	v_mfma_f32_16x16x32_bf16 v[90:93], v[146:149], v[170:173], v[90:93]
	v_mfma_f32_16x16x32_bf16 v[78:81], v[138:141], v[178:181], v[78:81]
	v_mfma_f32_16x16x32_bf16 v[74:77], v[146:149], v[178:181], v[74:77]
	s_setprio 0
	s_barrier
	s_add_i32 s25, 0, 0x14000
	v_lshl_add_u64 v[198:199], s[58:59], 0, v[0:1]
	s_add_i32 s58, s62, s29
	v_add_u32_e32 v194, s25, v136
	s_mov_b32 m0, s58
	ds_read_b128 v[182:185], v194
	ds_read_b128 v[186:189], v194 offset:1024
	ds_read_b128 v[190:193], v194 offset:2048
	ds_read_b128 v[194:197], v194 offset:3072
	global_load_lds_dwordx4 v[198:199], off
	v_lshl_add_u64 v[200:201], v[198:199], 0, s[92:93]
	s_add_i32 m0, s58, 0x2000
	s_nop 0
	global_load_lds_dwordx4 v[200:201], off
	s_barrier
	s_waitcnt lgkmcnt(0)
	s_setprio 1
	s_waitcnt lgkmcnt(0)
	v_mfma_f32_16x16x32_bf16 v[118:121], v[182:185], v[150:153], v[118:121]
	v_mfma_f32_16x16x32_bf16 v[114:117], v[190:193], v[150:153], v[114:117]
	v_mfma_f32_16x16x32_bf16 v[102:105], v[182:185], v[158:161], v[102:105]
	v_mfma_f32_16x16x32_bf16 v[98:101], v[190:193], v[158:161], v[98:101]
	v_mfma_f32_16x16x32_bf16 v[86:89], v[182:185], v[166:169], v[86:89]
	v_mfma_f32_16x16x32_bf16 v[82:85], v[190:193], v[166:169], v[82:85]
	v_mfma_f32_16x16x32_bf16 v[70:73], v[182:185], v[174:177], v[70:73]
	v_mfma_f32_16x16x32_bf16 v[66:69], v[190:193], v[174:177], v[66:69]
	v_mfma_f32_16x16x32_bf16 v[118:121], v[186:189], v[154:157], v[118:121]
	v_mfma_f32_16x16x32_bf16 v[114:117], v[194:197], v[154:157], v[114:117]
	v_mfma_f32_16x16x32_bf16 v[102:105], v[186:189], v[162:165], v[102:105]
	v_mfma_f32_16x16x32_bf16 v[98:101], v[194:197], v[162:165], v[98:101]
	v_mfma_f32_16x16x32_bf16 v[86:89], v[186:189], v[170:173], v[86:89]
	v_mfma_f32_16x16x32_bf16 v[82:85], v[194:197], v[170:173], v[82:85]
	v_mfma_f32_16x16x32_bf16 v[70:73], v[186:189], v[178:181], v[70:73]
	v_mfma_f32_16x16x32_bf16 v[66:69], v[194:197], v[178:181], v[66:69]
	s_setprio 0
	s_mov_b32 m0, s30
	v_lshl_add_u64 v[200:201], s[46:47], 0, v[0:1]
	s_barrier
	ds_read_b128 v[150:153], v137 offset:16384
	ds_read_b128 v[154:157], v137 offset:17408
	ds_read_b128 v[158:161], v137 offset:18432
	ds_read_b128 v[162:165], v137 offset:19456
	ds_read_b128 v[166:169], v137 offset:20480
	ds_read_b128 v[170:173], v137 offset:21504
	ds_read_b128 v[174:177], v137 offset:22528
	ds_read_b128 v[178:181], v137 offset:23552
	global_load_lds_dwordx4 v[200:201], off
	v_lshl_add_u64 v[202:203], v[200:201], 0, s[92:93]
	s_mov_b32 m0, s31
	s_nop 0
	global_load_lds_dwordx4 v[202:203], off
	s_barrier
	s_waitcnt lgkmcnt(0)
	s_setprio 1
	s_waitcnt lgkmcnt(0)
	v_mfma_f32_16x16x32_bf16 v[62:65], v[132:135], v[150:153], v[62:65]
	v_mfma_f32_16x16x32_bf16 v[58:61], v[142:145], v[150:153], v[58:61]
	v_mfma_f32_16x16x32_bf16 v[46:49], v[132:135], v[158:161], v[46:49]
	v_mfma_f32_16x16x32_bf16 v[42:45], v[142:145], v[158:161], v[42:45]
	v_mfma_f32_16x16x32_bf16 v[30:33], v[132:135], v[166:169], v[30:33]
	v_mfma_f32_16x16x32_bf16 v[26:29], v[142:145], v[166:169], v[26:29]
	v_mfma_f32_16x16x32_bf16 v[14:17], v[132:135], v[174:177], v[14:17]
	v_mfma_f32_16x16x32_bf16 v[10:13], v[142:145], v[174:177], v[10:13]
	v_mfma_f32_16x16x32_bf16 v[62:65], v[138:141], v[154:157], v[62:65]
	v_mfma_f32_16x16x32_bf16 v[58:61], v[146:149], v[154:157], v[58:61]
	v_mfma_f32_16x16x32_bf16 v[46:49], v[138:141], v[162:165], v[46:49]
	v_mfma_f32_16x16x32_bf16 v[42:45], v[146:149], v[162:165], v[42:45]
	v_mfma_f32_16x16x32_bf16 v[30:33], v[138:141], v[170:173], v[30:33]
	v_mfma_f32_16x16x32_bf16 v[26:29], v[146:149], v[170:173], v[26:29]
	v_mfma_f32_16x16x32_bf16 v[14:17], v[138:141], v[178:181], v[14:17]
	v_mfma_f32_16x16x32_bf16 v[10:13], v[146:149], v[178:181], v[10:13]
	s_setprio 0
	s_barrier
; #define PG8_STAGE(bufoff, gbase, voff) do { _Pragma("unroll") for (int _i = 0; _i < 2; ++_i) \
;         __builtin_amdgcn_global_load_lds((const unsigned*)((const char*)(gbase) + (size_t)_i * vst##voff + v##voff), (LAS unsigned*)(lds + (bufoff) + ldsw + _i * 8192), 16, 0, 0); } while (0)
; #define PG8_LDA(dst, b, h) do { _Pragma("unroll") for (int m = 0; m < 4; ++m) _Pragma("unroll") for (int k = 0; k < 2; ++k) dst[m][k] = *(const LAS bf16x8*)(lds + PG8_SA(b, h) + aoff + m * 2048 + k * 1024); } while (0)
; #define PG8_LDB(dst, b, h) do { _Pragma("unroll") for (int n = 0; n < 2; ++n) _Pragma("unroll") for (int k = 0; k < 2; ++k) dst[n][k] = *(const LAS bf16x8*)(lds + PG8_SB(b, h) + boff + n * 2048 + k * 1024); } while (0)
; #define PG8_MMA(ai, bj, At, Bt) do { __builtin_amdgcn_s_setprio(1); _Pragma("unroll") for (int m = 0; m < 4; ++m) _Pragma("unroll") for (int n = 0; n < 2; ++n) _Pragma("unroll") for (int k = 0; k < 2; ++k) \
;         acc[ai][bj][m][n] = __builtin_amdgcn_mfma_f32_16x16x32_bf16(Bt[n][k], At[m][k], acc[ai][bj][m][n], 0, 0, 0); __builtin_amdgcn_s_setprio(0); } while (0)
; #define PG8_WAIT_V(n) asm volatile("s_waitcnt vmcnt(" #n ")" ::: "memory")
; #define PG8_WAIT_L(n) asm volatile("s_waitcnt lgkmcnt(" #n ")" ::: "memory")
; #define PG8_BAR __builtin_amdgcn_s_barrier()
; #define PG8_SCHED __builtin_amdgcn_sched_barrier(0)
; template <class Epi>
; DI void gemm_phase(LAS unsigned char* lds, const Gemm g, const StaticOrder& S, const Epi& E, const int tid) {
;     ...
;             PG8_WAIT_V(6); PG8_BAR; PG8_MMA(1, 1, At, B1); PG8_BAR;
;             PG8_LDB(B0, 1, 0); PG8_SCHED; PG8_LDA(At, 1, 0); PG8_STAGE(PG8_SA(0, 1), a2 + hsA, offA);
;             PG8_WAIT_L(8); PG8_BAR; PG8_WAIT_L(0); PG8_MMA(0, 0, At, B0); PG8_BAR; PG8_SCHED;
;             PG8_LDB(B1, 1, 1); PG8_STAGE(PG8_SB(1, 0), b3, offB);
;             PG8_BAR; PG8_WAIT_L(0); PG8_MMA(0, 1, At, B1); PG8_BAR;
;             PG8_LDA(At, 1, 1); PG8_STAGE(PG8_SA(1, 0), a3, offA);
;             PG8_BAR; PG8_WAIT_L(0); PG8_MMA(1, 0, At, B0); PG8_BAR; PG8_SCHED;
	s_add_i32 s25, s25, s29
	v_lshl_add_u64 v[132:133], v[198:199], 0, s[4:5]
	s_mov_b32 m0, s25
	s_nop 0
	global_load_lds_dwordx4 v[132:133], off
	v_lshl_add_u64 v[132:133], v[198:199], 0, s[96:97]
	s_add_i32 m0, s25, 0x2000
	s_nop 0
	global_load_lds_dwordx4 v[132:133], off
	s_waitcnt vmcnt(6)
	s_barrier
	s_setprio 1
	v_mfma_f32_16x16x32_bf16 v[54:57], v[182:185], v[150:153], v[54:57]
	v_mfma_f32_16x16x32_bf16 v[50:53], v[190:193], v[150:153], v[50:53]
	v_mfma_f32_16x16x32_bf16 v[38:41], v[182:185], v[158:161], v[38:41]
	v_mfma_f32_16x16x32_bf16 v[34:37], v[190:193], v[158:161], v[34:37]
	v_mfma_f32_16x16x32_bf16 v[22:25], v[182:185], v[166:169], v[22:25]
	v_mfma_f32_16x16x32_bf16 v[18:21], v[190:193], v[166:169], v[18:21]
	v_mfma_f32_16x16x32_bf16 v[6:9], v[182:185], v[174:177], v[6:9]
	v_mfma_f32_16x16x32_bf16 v[2:5], v[190:193], v[174:177], v[2:5]
	v_mfma_f32_16x16x32_bf16 v[54:57], v[186:189], v[154:157], v[54:57]
	v_mfma_f32_16x16x32_bf16 v[50:53], v[194:197], v[154:157], v[50:53]
	v_mfma_f32_16x16x32_bf16 v[38:41], v[186:189], v[162:165], v[38:41]
	v_mfma_f32_16x16x32_bf16 v[34:37], v[194:197], v[162:165], v[34:37]
	v_mfma_f32_16x16x32_bf16 v[22:25], v[186:189], v[170:173], v[22:25]
	v_mfma_f32_16x16x32_bf16 v[18:21], v[194:197], v[170:173], v[18:21]
	v_mfma_f32_16x16x32_bf16 v[6:9], v[186:189], v[178:181], v[6:9]
	v_mfma_f32_16x16x32_bf16 v[2:5], v[194:197], v[178:181], v[2:5]
	s_setprio 0
	s_add_i32 s25, 0, 0x18000
	v_add_u32_e32 v146, s25, v136
	s_barrier
	ds_read_b128 v[132:135], v146
	ds_read_b128 v[138:141], v146 offset:1024
	ds_read_b128 v[142:145], v146 offset:2048
	ds_read_b128 v[146:149], v146 offset:3072
	s_mov_b32 m0, s34
	v_lshl_add_u64 v[182:183], v[200:201], 0, s[4:5]
	ds_read_b128 v[150:153], v137 offset:32768
	ds_read_b128 v[154:157], v137 offset:33792
	ds_read_b128 v[158:161], v137 offset:34816
	ds_read_b128 v[162:165], v137 offset:35840
	ds_read_b128 v[166:169], v137 offset:36864
	ds_read_b128 v[170:173], v137 offset:37888
	ds_read_b128 v[174:177], v137 offset:38912
	ds_read_b128 v[178:181], v137 offset:39936
	global_load_lds_dwordx4 v[182:183], off
	v_lshl_add_u64 v[182:183], v[200:201], 0, s[96:97]
	s_mov_b32 m0, s35
	s_nop 0
	global_load_lds_dwordx4 v[182:183], off
	s_waitcnt lgkmcnt(8)
	s_barrier
	s_waitcnt lgkmcnt(0)
	s_setprio 1
	s_waitcnt lgkmcnt(0)
	v_mfma_f32_16x16x32_bf16 v[126:129], v[132:135], v[150:153], v[126:129]
	v_mfma_f32_16x16x32_bf16 v[122:125], v[142:145], v[150:153], v[122:125]
	v_mfma_f32_16x16x32_bf16 v[110:113], v[132:135], v[158:161], v[110:113]
	v_mfma_f32_16x16x32_bf16 v[106:109], v[142:145], v[158:161], v[106:109]
	v_mfma_f32_16x16x32_bf16 v[94:97], v[132:135], v[166:169], v[94:97]
	v_mfma_f32_16x16x32_bf16 v[90:93], v[142:145], v[166:169], v[90:93]
	v_mfma_f32_16x16x32_bf16 v[78:81], v[132:135], v[174:177], v[78:81]
	v_mfma_f32_16x16x32_bf16 v[74:77], v[142:145], v[174:177], v[74:77]
	v_mfma_f32_16x16x32_bf16 v[126:129], v[138:141], v[154:157], v[126:129]
	v_mfma_f32_16x16x32_bf16 v[122:125], v[146:149], v[154:157], v[122:125]
	v_mfma_f32_16x16x32_bf16 v[110:113], v[138:141], v[162:165], v[110:113]
	v_mfma_f32_16x16x32_bf16 v[106:109], v[146:149], v[162:165], v[106:109]
	v_mfma_f32_16x16x32_bf16 v[94:97], v[138:141], v[170:173], v[94:97]
	v_mfma_f32_16x16x32_bf16 v[90:93], v[146:149], v[170:173], v[90:93]
	v_mfma_f32_16x16x32_bf16 v[78:81], v[138:141], v[178:181], v[78:81]
	v_mfma_f32_16x16x32_bf16 v[74:77], v[146:149], v[178:181], v[74:77]
	s_setprio 0
	s_barrier
	s_add_i32 s46, 0, 0x1c000
	s_add_i32 s25, s25, s29
	v_add_u32_e32 v194, s46, v136
	v_lshl_add_u64 v[202:203], v[198:199], 0, s[88:89]
	s_mov_b32 m0, s25
	ds_read_b128 v[182:185], v194
	ds_read_b128 v[186:189], v194 offset:1024
	ds_read_b128 v[190:193], v194 offset:2048
	ds_read_b128 v[194:197], v194 offset:3072
	global_load_lds_dwordx4 v[202:203], off
	v_lshl_add_u64 v[202:203], v[198:199], 0, s[0:1]
	s_add_i32 m0, s25, 0x2000
	s_nop 0
	global_load_lds_dwordx4 v[202:203], off
	s_barrier
	s_waitcnt lgkmcnt(0)
	s_setprio 1
	s_waitcnt lgkmcnt(0)
	v_mfma_f32_16x16x32_bf16 v[118:121], v[182:185], v[150:153], v[118:121]
	v_mfma_f32_16x16x32_bf16 v[114:117], v[190:193], v[150:153], v[114:117]
	v_mfma_f32_16x16x32_bf16 v[102:105], v[182:185], v[158:161], v[102:105]
	v_mfma_f32_16x16x32_bf16 v[98:101], v[190:193], v[158:161], v[98:101]
	v_mfma_f32_16x16x32_bf16 v[86:89], v[182:185], v[166:169], v[86:89]
	v_mfma_f32_16x16x32_bf16 v[82:85], v[190:193], v[166:169], v[82:85]
	v_mfma_f32_16x16x32_bf16 v[70:73], v[182:185], v[174:177], v[70:73]
	v_mfma_f32_16x16x32_bf16 v[66:69], v[190:193], v[174:177], v[66:69]
	v_mfma_f32_16x16x32_bf16 v[118:121], v[186:189], v[154:157], v[118:121]
	v_mfma_f32_16x16x32_bf16 v[114:117], v[194:197], v[154:157], v[114:117]
	v_mfma_f32_16x16x32_bf16 v[102:105], v[186:189], v[162:165], v[102:105]
	v_mfma_f32_16x16x32_bf16 v[98:101], v[194:197], v[162:165], v[98:101]
	v_mfma_f32_16x16x32_bf16 v[86:89], v[186:189], v[170:173], v[86:89]
	v_mfma_f32_16x16x32_bf16 v[82:85], v[194:197], v[170:173], v[82:85]
	v_mfma_f32_16x16x32_bf16 v[70:73], v[186:189], v[178:181], v[70:73]
	v_mfma_f32_16x16x32_bf16 v[66:69], v[194:197], v[178:181], v[66:69]
	s_setprio 0
	s_mov_b32 m0, s37
	v_lshl_add_u64 v[202:203], v[200:201], 0, s[88:89]
	s_barrier
	ds_read_b128 v[150:153], v137 offset:49152
	ds_read_b128 v[154:157], v137 offset:50176
	ds_read_b128 v[158:161], v137 offset:51200
	ds_read_b128 v[162:165], v137 offset:52224
	ds_read_b128 v[166:169], v137 offset:53248
	ds_read_b128 v[170:173], v137 offset:54272
	ds_read_b128 v[174:177], v137 offset:55296
	ds_read_b128 v[178:181], v137 offset:56320
	global_load_lds_dwordx4 v[202:203], off
	v_lshl_add_u64 v[200:201], v[200:201], 0, s[0:1]
	s_mov_b32 m0, s38
	s_nop 0
	global_load_lds_dwordx4 v[200:201], off
	s_barrier
; DI float bflo(unsigned w) { return __uint_as_float(w << 16); }
; DI float bfhi(unsigned w) { return __uint_as_float(w & 0xffff0000u); }
; #define PG8_STAGE(bufoff, gbase, voff) do { _Pragma("unroll") for (int _i = 0; _i < 2; ++_i) \
;         __builtin_amdgcn_global_load_lds((const unsigned*)((const char*)(gbase) + (size_t)_i * vst##voff + v##voff), (LAS unsigned*)(lds + (bufoff) + ldsw + _i * 8192), 16, 0, 0); } while (0)
; #define PG8_MMA(ai, bj, At, Bt) do { __builtin_amdgcn_s_setprio(1); _Pragma("unroll") for (int m = 0; m < 4; ++m) _Pragma("unroll") for (int n = 0; n < 2; ++n) _Pragma("unroll") for (int k = 0; k < 2; ++k) \
;         acc[ai][bj][m][n] = __builtin_amdgcn_mfma_f32_16x16x32_bf16(Bt[n][k], At[m][k], acc[ai][bj][m][n], 0, 0, 0); __builtin_amdgcn_s_setprio(0); } while (0)
; #define PG8_WAIT_V(n) asm volatile("s_waitcnt vmcnt(" #n ")" ::: "memory")
; #define PG8_BAR __builtin_amdgcn_s_barrier()
; template <class Epi>
; DI void gemm_phase(LAS unsigned char* lds, const Gemm g, const StaticOrder& S, const Epi& E, const int tid) {
;     ...
;             PG8_STAGE(PG8_SB(1, 1), b3 + hsB, offB);
;             PG8_WAIT_V(6); PG8_BAR; PG8_MMA(1, 1, At, B1); PG8_BAR;
;     DI void operator()(const AccT& acc, const Unit& u, int wr, int wc, int fr, int fq) const {
;     ...
;                 const int row = u.pm * 256 + ai * 128 + wr * 64 + m * 16 + fr; float ss = 0.f;
; #pragma unroll
;                 for (int bj = 0; bj < 2; ++bj)
; #pragma unroll
;                     for (int n = 0; n < 2; ++n) {
;                         const size_t o = (size_t)row * 1024 + u.pn * 256 + bj * 128 + wc * 32 + n * 16 + fq * 4;
;                         f32x4 hv; if (HBsrc) { const u32x2 hw = *(const u32x2*)(HBsrc + o); hv = (f32x4){bflo(hw.x), bfhi(hw.x), bflo(hw.y), bfhi(hw.y)}; } else hv = *(const f32x4*)(H + o);
;                         const f32x4 v = hv + acc[ai][bj][m][n];
;                         *(f32x4*)(H + o) = v; ss += (v[0] * v[0] + v[1] * v[1]) + (v[2] * v[2] + v[3] * v[3]);
;                     }
;                 if (sh2) { ss += __shfl_xor(ss, 16); ss += __shfl_xor(ss, 32); if (fq == 0) atomicAdd(sh2 + row, ss); }
	s_waitcnt lgkmcnt(0)
	s_setprio 1
	s_waitcnt lgkmcnt(0)
	v_mfma_f32_16x16x32_bf16 v[62:65], v[132:135], v[150:153], v[62:65]
	v_mfma_f32_16x16x32_bf16 v[58:61], v[142:145], v[150:153], v[58:61]
	v_mfma_f32_16x16x32_bf16 v[46:49], v[132:135], v[158:161], v[46:49]
	v_mfma_f32_16x16x32_bf16 v[42:45], v[142:145], v[158:161], v[42:45]
	v_mfma_f32_16x16x32_bf16 v[30:33], v[132:135], v[166:169], v[30:33]
	v_mfma_f32_16x16x32_bf16 v[26:29], v[142:145], v[166:169], v[26:29]
	v_mfma_f32_16x16x32_bf16 v[14:17], v[132:135], v[174:177], v[14:17]
	v_mfma_f32_16x16x32_bf16 v[10:13], v[142:145], v[174:177], v[10:13]
	v_mfma_f32_16x16x32_bf16 v[62:65], v[138:141], v[154:157], v[62:65]
	v_mfma_f32_16x16x32_bf16 v[58:61], v[146:149], v[154:157], v[58:61]
	v_mfma_f32_16x16x32_bf16 v[46:49], v[138:141], v[162:165], v[46:49]
	v_mfma_f32_16x16x32_bf16 v[42:45], v[146:149], v[162:165], v[42:45]
	v_mfma_f32_16x16x32_bf16 v[30:33], v[138:141], v[170:173], v[30:33]
	v_mfma_f32_16x16x32_bf16 v[26:29], v[146:149], v[170:173], v[26:29]
	v_mfma_f32_16x16x32_bf16 v[14:17], v[138:141], v[178:181], v[14:17]
	v_mfma_f32_16x16x32_bf16 v[10:13], v[146:149], v[178:181], v[10:13]
	s_setprio 0
	s_barrier
	s_add_i32 s25, s46, s29
	v_lshl_add_u64 v[132:133], v[198:199], 0, s[54:55]
	s_mov_b32 m0, s25
	s_nop 0
	global_load_lds_dwordx4 v[132:133], off
	v_lshl_add_u64 v[132:133], v[198:199], 0, s[80:81]
	s_add_i32 m0, s25, 0x2000
	s_nop 0
	global_load_lds_dwordx4 v[132:133], off
	s_waitcnt vmcnt(6)
	s_barrier
	s_setprio 1
	v_mfma_f32_16x16x32_bf16 v[54:57], v[182:185], v[150:153], v[54:57]
	v_mfma_f32_16x16x32_bf16 v[50:53], v[190:193], v[150:153], v[50:53]
	v_mfma_f32_16x16x32_bf16 v[38:41], v[182:185], v[158:161], v[38:41]
	v_mfma_f32_16x16x32_bf16 v[34:37], v[190:193], v[158:161], v[34:37]
	v_mfma_f32_16x16x32_bf16 v[22:25], v[182:185], v[166:169], v[22:25]
	v_mfma_f32_16x16x32_bf16 v[18:21], v[190:193], v[166:169], v[18:21]
	v_mfma_f32_16x16x32_bf16 v[6:9], v[182:185], v[174:177], v[6:9]
	v_mfma_f32_16x16x32_bf16 v[2:5], v[190:193], v[174:177], v[2:5]
	v_mfma_f32_16x16x32_bf16 v[54:57], v[186:189], v[154:157], v[54:57]
	v_mfma_f32_16x16x32_bf16 v[50:53], v[194:197], v[154:157], v[50:53]
	v_mfma_f32_16x16x32_bf16 v[38:41], v[186:189], v[162:165], v[38:41]
	v_mfma_f32_16x16x32_bf16 v[34:37], v[194:197], v[162:165], v[34:37]
	v_mfma_f32_16x16x32_bf16 v[22:25], v[186:189], v[170:173], v[22:25]
	v_mfma_f32_16x16x32_bf16 v[18:21], v[194:197], v[170:173], v[18:21]
	v_mfma_f32_16x16x32_bf16 v[6:9], v[186:189], v[178:181], v[6:9]
	v_mfma_f32_16x16x32_bf16 v[2:5], v[194:197], v[178:181], v[2:5]
	s_setprio 0
	s_add_i32 s24, s24, 2
	s_add_u32 s6, s6, 0x100
	s_addc_u32 s7, s7, 0
	s_add_u32 s22, s22, 0x100
	s_addc_u32 s23, s23, 0
	s_cmp_gt_u32 s24, 19
	s_barrier
	s_cbranch_scc0 .LBB0_1863
	s_lshl_b32 s6, s43, 8
	s_add_i32 s6, s6, s36
	v_mbcnt_lo_u32_b32 v133, -1, 0
	v_mbcnt_hi_u32_b32 v133, -1, v133
	s_nop 0
	v_and_or_b32 v132, v133, 15, s6
	s_lshl_b32 s6, s42, 8
	v_ashrrev_i32_e32 v134, 2, v133
	s_ashr_i32 s7, s6, 31
	v_and_b32_e32 v134, -4, v134
	v_ashrrev_i32_e32 v135, 31, v134
	s_or_b64 s[6:7], s[6:7], s[90:91]
	v_cmp_gt_u32_e32 vcc, 16, v133
	v_ashrrev_i32_e32 v133, 31, v132
	v_lshl_add_u64 v[134:135], s[6:7], 0, v[134:135]
	v_lshlrev_b64 v[138:139], 10, v[132:133]
	v_lshl_add_u64 v[138:139], v[134:135], 0, v[138:139]
	v_lshl_add_u64 v[142:143], v[138:139], 2, s[8:9]
	global_load_dwordx4 v[150:153], v[142:143], off
	global_load_dwordx4 v[154:157], v[142:143], off offset:64
	global_load_dwordx4 v[158:161], v[142:143], off offset:512
	global_load_dwordx4 v[162:165], v[142:143], off offset:576
	s_waitcnt vmcnt(3)
	s_nop 0
	v_mov_b32_e32 v138, v150
	v_mov_b32_e32 v139, v151
	v_mov_b32_e32 v140, v152
	v_mov_b32_e32 v141, v153
	v_pk_add_f32 v[128:129], v[128:129], v[140:141]
	v_pk_add_f32 v[126:127], v[126:127], v[138:139]
	global_store_dwordx4 v[142:143], v[126:129], off
	s_nop 1
	v_mul_f32_e32 v127, v127, v127
	v_fmac_f32_e32 v127, v126, v126
	v_mul_f32_e32 v126, v129, v129
	v_fmac_f32_e32 v126, v128, v128
	v_add_f32_e32 v138, v127, v126
	s_waitcnt vmcnt(3)
	s_nop 0
	v_mov_b32_e32 v126, v154
	v_mov_b32_e32 v127, v155
	v_mov_b32_e32 v128, v156
	v_mov_b32_e32 v129, v157
	v_pk_add_f32 v[124:125], v[124:125], v[128:129]
	v_pk_add_f32 v[122:123], v[122:123], v[126:127]
	global_store_dwordx4 v[142:143], v[122:125], off offset:64
	s_nop 1
	v_mul_f32_e32 v123, v123, v123
	v_fmac_f32_e32 v123, v122, v122
	v_mul_f32_e32 v122, v125, v125
	v_fmac_f32_e32 v122, v124, v124
	v_add_f32_e32 v122, v123, v122
	v_add_f32_e32 v126, v138, v122
	s_waitcnt vmcnt(3)
	s_nop 0
	v_mov_b32_e32 v122, v158
	v_mov_b32_e32 v123, v159
	v_mov_b32_e32 v124, v160
	v_mov_b32_e32 v125, v161
	v_pk_add_f32 v[120:121], v[120:121], v[124:125]
	v_pk_add_f32 v[118:119], v[118:119], v[122:123]
	global_store_dwordx4 v[142:143], v[118:121], off offset:512
	s_nop 1
	v_mul_f32_e32 v119, v119, v119
	v_fmac_f32_e32 v119, v118, v118
	v_mul_f32_e32 v118, v121, v121
	v_fmac_f32_e32 v118, v120, v120
	v_add_f32_e32 v118, v119, v118
	v_add_f32_e32 v122, v126, v118
	s_waitcnt vmcnt(3)
	s_nop 0
	v_mov_b32_e32 v118, v162
	v_mov_b32_e32 v119, v163
	v_mov_b32_e32 v120, v164
	v_mov_b32_e32 v121, v165
	v_pk_add_f32 v[116:117], v[116:117], v[120:121]
	v_pk_add_f32 v[114:115], v[114:115], v[118:119]
	global_store_dwordx4 v[142:143], v[114:117], off offset:576
	s_nop 1
	v_mul_f32_e32 v115, v115, v115
	v_fmac_f32_e32 v115, v114, v114
	v_mul_f32_e32 v114, v117, v117
	v_fmac_f32_e32 v114, v116, v116
	v_and_b32_e32 v116, 64, v226
	v_add_f32_e32 v114, v115, v114
	v_xor_b32_e32 v115, 16, v226
	v_add_u32_e32 v117, 64, v116
	v_cmp_lt_i32_e64 s[6:7], v115, v117
	v_add_f32_e32 v114, v122, v114
	s_nop 0
	v_cndmask_b32_e64 v115, v226, v115, s[6:7]
	v_lshlrev_b32_e32 v116, 2, v115
	ds_bpermute_b32 v115, v116, v114
	s_waitcnt lgkmcnt(0)
	v_add_f32_e32 v114, v114, v115
	v_xor_b32_e32 v115, 32, v226
	v_cmp_lt_i32_e64 s[6:7], v115, v117
	s_nop 1
	v_cndmask_b32_e64 v115, v226, v115, s[6:7]
	v_lshlrev_b32_e32 v117, 2, v115
	ds_bpermute_b32 v115, v117, v114
	s_and_saveexec_b64 s[6:7], vcc
	s_cbranch_execz .LBB0_1866
	s_waitcnt lgkmcnt(0)
	v_add_f32_e32 v118, v114, v115
	v_lshl_add_u64 v[114:115], v[132:133], 2, s[10:11]
	global_atomic_add_f32 v[114:115], v118, off
; DI float bflo(unsigned w) { return __uint_as_float(w << 16); }
; DI float bfhi(unsigned w) { return __uint_as_float(w & 0xffff0000u); }
;     DI void operator()(const AccT& acc, const Unit& u, int wr, int wc, int fr, int fq) const {
;     ...
;                 const int row = u.pm * 256 + ai * 128 + wr * 64 + m * 16 + fr; float ss = 0.f;
; #pragma unroll
;                 for (int bj = 0; bj < 2; ++bj)
; #pragma unroll
;                     for (int n = 0; n < 2; ++n) {
;                         const size_t o = (size_t)row * 1024 + u.pn * 256 + bj * 128 + wc * 32 + n * 16 + fq * 4;
;                         f32x4 hv; if (HBsrc) { const u32x2 hw = *(const u32x2*)(HBsrc + o); hv = (f32x4){bflo(hw.x), bfhi(hw.x), bflo(hw.y), bfhi(hw.y)}; } else hv = *(const f32x4*)(H + o);
;                         const f32x4 v = hv + acc[ai][bj][m][n];
;                         *(f32x4*)(H + o) = v; ss += (v[0] * v[0] + v[1] * v[1]) + (v[2] * v[2] + v[3] * v[3]);
;                     }
;                 if (sh2) { ss += __shfl_xor(ss, 16); ss += __shfl_xor(ss, 32); if (fq == 0) atomicAdd(sh2 + row, ss); }
.LBB0_1866:
	s_or_b64 exec, exec, s[6:7]
	v_or_b32_e32 v114, 16, v132
	s_waitcnt lgkmcnt(0)
	v_ashrrev_i32_e32 v115, 31, v114
	v_lshlrev_b64 v[118:119], 10, v[114:115]
	v_lshl_add_u64 v[118:119], v[118:119], 0, v[134:135]
	v_lshl_add_u64 v[122:123], v[118:119], 2, s[8:9]
	global_load_dwordx4 v[150:153], v[122:123], off
	global_load_dwordx4 v[154:157], v[122:123], off offset:64
	global_load_dwordx4 v[158:161], v[122:123], off offset:512
	global_load_dwordx4 v[162:165], v[122:123], off offset:576
	s_waitcnt vmcnt(3)
	s_nop 0
	v_mov_b32_e32 v118, v150
	v_mov_b32_e32 v119, v151
	v_mov_b32_e32 v120, v152
	v_mov_b32_e32 v121, v153
	v_pk_add_f32 v[112:113], v[112:113], v[120:121]
	v_pk_add_f32 v[110:111], v[110:111], v[118:119]
	global_store_dwordx4 v[122:123], v[110:113], off
	s_nop 1
	v_mul_f32_e32 v111, v111, v111
	v_fmac_f32_e32 v111, v110, v110
	v_mul_f32_e32 v110, v113, v113
	v_fmac_f32_e32 v110, v112, v112
	v_add_f32_e32 v118, v111, v110
	s_waitcnt vmcnt(3)
	s_nop 0
	v_mov_b32_e32 v110, v154
	v_mov_b32_e32 v111, v155
	v_mov_b32_e32 v112, v156
	v_mov_b32_e32 v113, v157
	v_pk_add_f32 v[108:109], v[108:109], v[112:113]
	v_pk_add_f32 v[106:107], v[106:107], v[110:111]
	global_store_dwordx4 v[122:123], v[106:109], off offset:64
	s_nop 1
	v_mul_f32_e32 v107, v107, v107
	v_fmac_f32_e32 v107, v106, v106
	v_mul_f32_e32 v106, v109, v109
	v_fmac_f32_e32 v106, v108, v108
	v_add_f32_e32 v106, v107, v106
	v_add_f32_e32 v110, v118, v106
	s_waitcnt vmcnt(3)
	s_nop 0
	v_mov_b32_e32 v106, v158
	v_mov_b32_e32 v107, v159
	v_mov_b32_e32 v108, v160
	v_mov_b32_e32 v109, v161
	v_pk_add_f32 v[104:105], v[104:105], v[108:109]
	v_pk_add_f32 v[102:103], v[102:103], v[106:107]
	global_store_dwordx4 v[122:123], v[102:105], off offset:512
	s_nop 1
	v_mul_f32_e32 v103, v103, v103
	v_fmac_f32_e32 v103, v102, v102
	v_mul_f32_e32 v102, v105, v105
	v_fmac_f32_e32 v102, v104, v104
	v_add_f32_e32 v102, v103, v102
	v_add_f32_e32 v106, v110, v102
	s_waitcnt vmcnt(3)
	s_nop 0
	v_mov_b32_e32 v102, v162
	v_mov_b32_e32 v103, v163
	v_mov_b32_e32 v104, v164
	v_mov_b32_e32 v105, v165
	v_pk_add_f32 v[100:101], v[100:101], v[104:105]
	v_pk_add_f32 v[98:99], v[98:99], v[102:103]
	global_store_dwordx4 v[122:123], v[98:101], off offset:576
	s_nop 1
	v_mul_f32_e32 v99, v99, v99
	v_fmac_f32_e32 v99, v98, v98
	v_mul_f32_e32 v98, v101, v101
	v_fmac_f32_e32 v98, v100, v100
	v_add_f32_e32 v98, v99, v98
	v_add_f32_e32 v98, v106, v98
	ds_bpermute_b32 v99, v116, v98
	s_waitcnt lgkmcnt(0)
	v_add_f32_e32 v98, v98, v99
	ds_bpermute_b32 v99, v117, v98
	s_and_saveexec_b64 s[6:7], vcc
	s_cbranch_execz .LBB0_1868
	s_waitcnt lgkmcnt(0)
	v_add_f32_e32 v100, v98, v99
	v_lshl_add_u64 v[98:99], v[114:115], 2, s[10:11]
	global_atomic_add_f32 v[98:99], v100, off
.LBB0_1868:
	s_or_b64 exec, exec, s[6:7]
	v_or_b32_e32 v98, 32, v132
	s_waitcnt lgkmcnt(0)
	v_ashrrev_i32_e32 v99, 31, v98
	v_lshlrev_b64 v[100:101], 10, v[98:99]
	v_lshl_add_u64 v[100:101], v[100:101], 0, v[134:135]
	v_lshl_add_u64 v[104:105], v[100:101], 2, s[8:9]
	global_load_dwordx4 v[150:153], v[104:105], off
	global_load_dwordx4 v[154:157], v[104:105], off offset:64
	global_load_dwordx4 v[158:161], v[104:105], off offset:512
	global_load_dwordx4 v[162:165], v[104:105], off offset:576
	s_waitcnt vmcnt(3)
	s_nop 0
	v_mov_b32_e32 v100, v150
	v_mov_b32_e32 v101, v151
	v_mov_b32_e32 v102, v152
	v_mov_b32_e32 v103, v153
	v_pk_add_f32 v[96:97], v[96:97], v[102:103]
	v_pk_add_f32 v[94:95], v[94:95], v[100:101]
	global_store_dwordx4 v[104:105], v[94:97], off
	s_nop 1
	v_mul_f32_e32 v95, v95, v95
	v_fmac_f32_e32 v95, v94, v94
	v_mul_f32_e32 v94, v97, v97
	v_fmac_f32_e32 v94, v96, v96
	v_add_f32_e32 v100, v95, v94
	s_waitcnt vmcnt(3)
	s_nop 0
	v_mov_b32_e32 v94, v154
	v_mov_b32_e32 v95, v155
	v_mov_b32_e32 v96, v156
	v_mov_b32_e32 v97, v157
	v_pk_add_f32 v[92:93], v[92:93], v[96:97]
	v_pk_add_f32 v[90:91], v[90:91], v[94:95]
	global_store_dwordx4 v[104:105], v[90:93], off offset:64
	s_nop 1
	v_mul_f32_e32 v91, v91, v91
	v_fmac_f32_e32 v91, v90, v90
	v_mul_f32_e32 v90, v93, v93
	v_fmac_f32_e32 v90, v92, v92
	v_add_f32_e32 v90, v91, v90
	v_add_f32_e32 v94, v100, v90
	s_waitcnt vmcnt(3)
	s_nop 0
	v_mov_b32_e32 v90, v158
	v_mov_b32_e32 v91, v159
	v_mov_b32_e32 v92, v160
	v_mov_b32_e32 v93, v161
	v_pk_add_f32 v[88:89], v[88:89], v[92:93]
	v_pk_add_f32 v[86:87], v[86:87], v[90:91]
	global_store_dwordx4 v[104:105], v[86:89], off offset:512
	s_nop 1
	v_mul_f32_e32 v87, v87, v87
	v_fmac_f32_e32 v87, v86, v86
	v_mul_f32_e32 v86, v89, v89
	v_fmac_f32_e32 v86, v88, v88
	v_add_f32_e32 v86, v87, v86
	v_add_f32_e32 v90, v94, v86
	s_waitcnt vmcnt(3)
	s_nop 0
	v_mov_b32_e32 v86, v162
	v_mov_b32_e32 v87, v163
	v_mov_b32_e32 v88, v164
	v_mov_b32_e32 v89, v165
	v_pk_add_f32 v[84:85], v[84:85], v[88:89]
	v_pk_add_f32 v[82:83], v[82:83], v[86:87]
	global_store_dwordx4 v[104:105], v[82:85], off offset:576
	s_nop 1
	v_mul_f32_e32 v83, v83, v83
	v_fmac_f32_e32 v83, v82, v82
	v_mul_f32_e32 v82, v85, v85
	v_fmac_f32_e32 v82, v84, v84
	v_add_f32_e32 v82, v83, v82
	v_add_f32_e32 v82, v90, v82
	ds_bpermute_b32 v83, v116, v82
	s_waitcnt lgkmcnt(0)
	v_add_f32_e32 v82, v82, v83
	ds_bpermute_b32 v83, v117, v82
	s_and_saveexec_b64 s[6:7], vcc
	s_cbranch_execz .LBB0_1870
	s_waitcnt lgkmcnt(0)
	v_add_f32_e32 v84, v82, v83
	v_lshl_add_u64 v[82:83], v[98:99], 2, s[10:11]
	global_atomic_add_f32 v[82:83], v84, off
; DI float bflo(unsigned w) { return __uint_as_float(w << 16); }
; DI float bfhi(unsigned w) { return __uint_as_float(w & 0xffff0000u); }
;     DI void operator()(const AccT& acc, const Unit& u, int wr, int wc, int fr, int fq) const {
;     ...
;                 const int row = u.pm * 256 + ai * 128 + wr * 64 + m * 16 + fr; float ss = 0.f;
; #pragma unroll
;                 for (int bj = 0; bj < 2; ++bj)
; #pragma unroll
;                     for (int n = 0; n < 2; ++n) {
;                         const size_t o = (size_t)row * 1024 + u.pn * 256 + bj * 128 + wc * 32 + n * 16 + fq * 4;
;                         f32x4 hv; if (HBsrc) { const u32x2 hw = *(const u32x2*)(HBsrc + o); hv = (f32x4){bflo(hw.x), bfhi(hw.x), bflo(hw.y), bfhi(hw.y)}; } else hv = *(const f32x4*)(H + o);
;                         const f32x4 v = hv + acc[ai][bj][m][n];
;                         *(f32x4*)(H + o) = v; ss += (v[0] * v[0] + v[1] * v[1]) + (v[2] * v[2] + v[3] * v[3]);
;                     }
;                 if (sh2) { ss += __shfl_xor(ss, 16); ss += __shfl_xor(ss, 32); if (fq == 0) atomicAdd(sh2 + row, ss); }
.LBB0_1870:
	s_or_b64 exec, exec, s[6:7]
	v_or_b32_e32 v82, 48, v132
	s_waitcnt lgkmcnt(0)
	v_ashrrev_i32_e32 v83, 31, v82
	v_lshlrev_b64 v[84:85], 10, v[82:83]
	v_lshl_add_u64 v[84:85], v[84:85], 0, v[134:135]
	v_lshl_add_u64 v[88:89], v[84:85], 2, s[8:9]
	global_load_dwordx4 v[150:153], v[88:89], off
	global_load_dwordx4 v[154:157], v[88:89], off offset:64
	global_load_dwordx4 v[158:161], v[88:89], off offset:512
	global_load_dwordx4 v[162:165], v[88:89], off offset:576
	s_waitcnt vmcnt(3)
	s_nop 0
	v_mov_b32_e32 v84, v150
	v_mov_b32_e32 v85, v151
	v_mov_b32_e32 v86, v152
	v_mov_b32_e32 v87, v153
	v_pk_add_f32 v[80:81], v[80:81], v[86:87]
	v_pk_add_f32 v[78:79], v[78:79], v[84:85]
	global_store_dwordx4 v[88:89], v[78:81], off
	s_nop 1
	v_mul_f32_e32 v79, v79, v79
	v_fmac_f32_e32 v79, v78, v78
	v_mul_f32_e32 v78, v81, v81
	v_fmac_f32_e32 v78, v80, v80
	v_add_f32_e32 v84, v79, v78
	s_waitcnt vmcnt(3)
	s_nop 0
	v_mov_b32_e32 v78, v154
	v_mov_b32_e32 v79, v155
	v_mov_b32_e32 v80, v156
	v_mov_b32_e32 v81, v157
	v_pk_add_f32 v[76:77], v[76:77], v[80:81]
	v_pk_add_f32 v[74:75], v[74:75], v[78:79]
	global_store_dwordx4 v[88:89], v[74:77], off offset:64
	s_nop 1
	v_mul_f32_e32 v75, v75, v75
	v_fmac_f32_e32 v75, v74, v74
	v_mul_f32_e32 v74, v77, v77
	v_fmac_f32_e32 v74, v76, v76
	v_add_f32_e32 v74, v75, v74
	v_add_f32_e32 v78, v84, v74
	s_waitcnt vmcnt(3)
	s_nop 0
	v_mov_b32_e32 v74, v158
	v_mov_b32_e32 v75, v159
	v_mov_b32_e32 v76, v160
	v_mov_b32_e32 v77, v161
	v_pk_add_f32 v[72:73], v[72:73], v[76:77]
	v_pk_add_f32 v[70:71], v[70:71], v[74:75]
	global_store_dwordx4 v[88:89], v[70:73], off offset:512
	s_nop 1
	v_mul_f32_e32 v71, v71, v71
	v_fmac_f32_e32 v71, v70, v70
	v_mul_f32_e32 v70, v73, v73
	v_fmac_f32_e32 v70, v72, v72
	v_add_f32_e32 v70, v71, v70
	v_add_f32_e32 v74, v78, v70
	s_waitcnt vmcnt(3)
	s_nop 0
	v_mov_b32_e32 v70, v162
	v_mov_b32_e32 v71, v163
	v_mov_b32_e32 v72, v164
	v_mov_b32_e32 v73, v165
	v_pk_add_f32 v[68:69], v[68:69], v[72:73]
	v_pk_add_f32 v[66:67], v[66:67], v[70:71]
	global_store_dwordx4 v[88:89], v[66:69], off offset:576
	s_nop 1
	v_mul_f32_e32 v67, v67, v67
	v_fmac_f32_e32 v67, v66, v66
	v_mul_f32_e32 v66, v69, v69
	v_fmac_f32_e32 v66, v68, v68
	v_add_f32_e32 v66, v67, v66
	v_add_f32_e32 v66, v74, v66
	ds_bpermute_b32 v67, v116, v66
	s_waitcnt lgkmcnt(0)
	v_add_f32_e32 v66, v66, v67
	ds_bpermute_b32 v67, v117, v66
	s_and_saveexec_b64 s[6:7], vcc
	s_cbranch_execz .LBB0_1872
	s_waitcnt lgkmcnt(0)
	v_add_f32_e32 v68, v66, v67
	v_lshl_add_u64 v[66:67], v[82:83], 2, s[10:11]
	global_atomic_add_f32 v[66:67], v68, off
.LBB0_1872:
	s_or_b64 exec, exec, s[6:7]
	v_add_u32_e32 v66, 0x80, v132
	s_waitcnt lgkmcnt(0)
	v_ashrrev_i32_e32 v67, 31, v66
	v_lshlrev_b64 v[68:69], 10, v[66:67]
	v_lshl_add_u64 v[68:69], v[68:69], 0, v[134:135]
	v_lshl_add_u64 v[72:73], v[68:69], 2, s[8:9]
	global_load_dwordx4 v[150:153], v[72:73], off
	global_load_dwordx4 v[154:157], v[72:73], off offset:64
	global_load_dwordx4 v[158:161], v[72:73], off offset:512
	global_load_dwordx4 v[162:165], v[72:73], off offset:576
	s_waitcnt vmcnt(3)
	s_nop 0
	v_mov_b32_e32 v68, v150
	v_mov_b32_e32 v69, v151
	v_mov_b32_e32 v70, v152
	v_mov_b32_e32 v71, v153
	v_pk_add_f32 v[64:65], v[64:65], v[70:71]
	v_pk_add_f32 v[62:63], v[62:63], v[68:69]
	global_store_dwordx4 v[72:73], v[62:65], off
	s_nop 1
	v_mul_f32_e32 v63, v63, v63
	v_fmac_f32_e32 v63, v62, v62
	v_mul_f32_e32 v62, v65, v65
	v_fmac_f32_e32 v62, v64, v64
	v_add_f32_e32 v68, v63, v62
	s_waitcnt vmcnt(3)
	s_nop 0
	v_mov_b32_e32 v62, v154
	v_mov_b32_e32 v63, v155
	v_mov_b32_e32 v64, v156
	v_mov_b32_e32 v65, v157
	v_pk_add_f32 v[60:61], v[60:61], v[64:65]
	v_pk_add_f32 v[58:59], v[58:59], v[62:63]
	global_store_dwordx4 v[72:73], v[58:61], off offset:64
	s_nop 1
	v_mul_f32_e32 v59, v59, v59
	v_fmac_f32_e32 v59, v58, v58
	v_mul_f32_e32 v58, v61, v61
	v_fmac_f32_e32 v58, v60, v60
	v_add_f32_e32 v58, v59, v58
	v_add_f32_e32 v62, v68, v58
	s_waitcnt vmcnt(3)
	s_nop 0
	v_mov_b32_e32 v58, v158
	v_mov_b32_e32 v59, v159
	v_mov_b32_e32 v60, v160
	v_mov_b32_e32 v61, v161
	v_pk_add_f32 v[56:57], v[56:57], v[60:61]
	v_pk_add_f32 v[54:55], v[54:55], v[58:59]
	global_store_dwordx4 v[72:73], v[54:57], off offset:512
	s_nop 1
	v_mul_f32_e32 v55, v55, v55
	v_fmac_f32_e32 v55, v54, v54
	v_mul_f32_e32 v54, v57, v57
	v_fmac_f32_e32 v54, v56, v56
	v_add_f32_e32 v54, v55, v54
	v_add_f32_e32 v58, v62, v54
	s_waitcnt vmcnt(3)
	s_nop 0
	v_mov_b32_e32 v54, v162
	v_mov_b32_e32 v55, v163
	v_mov_b32_e32 v56, v164
	v_mov_b32_e32 v57, v165
	v_pk_add_f32 v[52:53], v[52:53], v[56:57]
	v_pk_add_f32 v[50:51], v[50:51], v[54:55]
	global_store_dwordx4 v[72:73], v[50:53], off offset:576
	s_nop 1
	v_mul_f32_e32 v51, v51, v51
	v_fmac_f32_e32 v51, v50, v50
	v_mul_f32_e32 v50, v53, v53
	v_fmac_f32_e32 v50, v52, v52
	v_add_f32_e32 v50, v51, v50
	v_add_f32_e32 v50, v58, v50
	ds_bpermute_b32 v51, v116, v50
	s_waitcnt lgkmcnt(0)
	v_add_f32_e32 v50, v50, v51
	ds_bpermute_b32 v51, v117, v50
	s_and_saveexec_b64 s[6:7], vcc
	s_cbranch_execz .LBB0_1874
	s_waitcnt lgkmcnt(0)
	v_add_f32_e32 v52, v50, v51
	v_lshl_add_u64 v[50:51], v[66:67], 2, s[10:11]
	global_atomic_add_f32 v[50:51], v52, off
; DI float bflo(unsigned w) { return __uint_as_float(w << 16); }
; DI float bfhi(unsigned w) { return __uint_as_float(w & 0xffff0000u); }
;     DI void operator()(const AccT& acc, const Unit& u, int wr, int wc, int fr, int fq) const {
;     ...
;                 const int row = u.pm * 256 + ai * 128 + wr * 64 + m * 16 + fr; float ss = 0.f;
; #pragma unroll
;                 for (int bj = 0; bj < 2; ++bj)
; #pragma unroll
;                     for (int n = 0; n < 2; ++n) {
;                         const size_t o = (size_t)row * 1024 + u.pn * 256 + bj * 128 + wc * 32 + n * 16 + fq * 4;
;                         f32x4 hv; if (HBsrc) { const u32x2 hw = *(const u32x2*)(HBsrc + o); hv = (f32x4){bflo(hw.x), bfhi(hw.x), bflo(hw.y), bfhi(hw.y)}; } else hv = *(const f32x4*)(H + o);
;                         const f32x4 v = hv + acc[ai][bj][m][n];
;                         *(f32x4*)(H + o) = v; ss += (v[0] * v[0] + v[1] * v[1]) + (v[2] * v[2] + v[3] * v[3]);
;                     }
;                 if (sh2) { ss += __shfl_xor(ss, 16); ss += __shfl_xor(ss, 32); if (fq == 0) atomicAdd(sh2 + row, ss); }
.LBB0_1874:
	s_or_b64 exec, exec, s[6:7]
	v_add_u32_e32 v50, 0x90, v132
	s_waitcnt lgkmcnt(0)
	v_ashrrev_i32_e32 v51, 31, v50
	v_lshlrev_b64 v[52:53], 10, v[50:51]
	v_lshl_add_u64 v[52:53], v[52:53], 0, v[134:135]
	v_lshl_add_u64 v[56:57], v[52:53], 2, s[8:9]
	global_load_dwordx4 v[150:153], v[56:57], off
	global_load_dwordx4 v[154:157], v[56:57], off offset:64
	global_load_dwordx4 v[158:161], v[56:57], off offset:512
	global_load_dwordx4 v[162:165], v[56:57], off offset:576
	s_waitcnt vmcnt(3)
	s_nop 0
	v_mov_b32_e32 v52, v150
	v_mov_b32_e32 v53, v151
	v_mov_b32_e32 v54, v152
	v_mov_b32_e32 v55, v153
	v_pk_add_f32 v[48:49], v[48:49], v[54:55]
	v_pk_add_f32 v[46:47], v[46:47], v[52:53]
	global_store_dwordx4 v[56:57], v[46:49], off
	s_nop 1
	v_mul_f32_e32 v47, v47, v47
	v_fmac_f32_e32 v47, v46, v46
	v_mul_f32_e32 v46, v49, v49
	v_fmac_f32_e32 v46, v48, v48
	v_add_f32_e32 v52, v47, v46
	s_waitcnt vmcnt(3)
	s_nop 0
	v_mov_b32_e32 v46, v154
	v_mov_b32_e32 v47, v155
	v_mov_b32_e32 v48, v156
	v_mov_b32_e32 v49, v157
	v_pk_add_f32 v[44:45], v[44:45], v[48:49]
	v_pk_add_f32 v[42:43], v[42:43], v[46:47]
	global_store_dwordx4 v[56:57], v[42:45], off offset:64
	s_nop 1
	v_mul_f32_e32 v43, v43, v43
	v_fmac_f32_e32 v43, v42, v42
	v_mul_f32_e32 v42, v45, v45
	v_fmac_f32_e32 v42, v44, v44
	v_add_f32_e32 v42, v43, v42
	v_add_f32_e32 v46, v52, v42
	s_waitcnt vmcnt(3)
	s_nop 0
	v_mov_b32_e32 v42, v158
	v_mov_b32_e32 v43, v159
	v_mov_b32_e32 v44, v160
	v_mov_b32_e32 v45, v161
	v_pk_add_f32 v[40:41], v[40:41], v[44:45]
	v_pk_add_f32 v[38:39], v[38:39], v[42:43]
	global_store_dwordx4 v[56:57], v[38:41], off offset:512
	s_nop 1
	v_mul_f32_e32 v39, v39, v39
	v_fmac_f32_e32 v39, v38, v38
	v_mul_f32_e32 v38, v41, v41
	v_fmac_f32_e32 v38, v40, v40
	v_add_f32_e32 v38, v39, v38
	v_add_f32_e32 v42, v46, v38
	s_waitcnt vmcnt(3)
	s_nop 0
	v_mov_b32_e32 v38, v162
	v_mov_b32_e32 v39, v163
	v_mov_b32_e32 v40, v164
	v_mov_b32_e32 v41, v165
	v_pk_add_f32 v[36:37], v[36:37], v[40:41]
	v_pk_add_f32 v[34:35], v[34:35], v[38:39]
	global_store_dwordx4 v[56:57], v[34:37], off offset:576
	s_nop 1
	v_mul_f32_e32 v35, v35, v35
	v_fmac_f32_e32 v35, v34, v34
	v_mul_f32_e32 v34, v37, v37
	v_fmac_f32_e32 v34, v36, v36
	v_add_f32_e32 v34, v35, v34
	v_add_f32_e32 v34, v42, v34
	ds_bpermute_b32 v35, v116, v34
	s_waitcnt lgkmcnt(0)
	v_add_f32_e32 v34, v34, v35
	ds_bpermute_b32 v35, v117, v34
	s_and_saveexec_b64 s[6:7], vcc
	s_cbranch_execz .LBB0_1876
	s_waitcnt lgkmcnt(0)
	v_add_f32_e32 v36, v34, v35
	v_lshl_add_u64 v[34:35], v[50:51], 2, s[10:11]
	global_atomic_add_f32 v[34:35], v36, off
; DI float bflo(unsigned w) { return __uint_as_float(w << 16); }
; DI float bfhi(unsigned w) { return __uint_as_float(w & 0xffff0000u); }
;     DI void operator()(const AccT& acc, const Unit& u, int wr, int wc, int fr, int fq) const {
;     ...
;                 const int row = u.pm * 256 + ai * 128 + wr * 64 + m * 16 + fr; float ss = 0.f;
; #pragma unroll
;                 for (int bj = 0; bj < 2; ++bj)
; #pragma unroll
;                     for (int n = 0; n < 2; ++n) {
;                         const size_t o = (size_t)row * 1024 + u.pn * 256 + bj * 128 + wc * 32 + n * 16 + fq * 4;
;                         f32x4 hv; if (HBsrc) { const u32x2 hw = *(const u32x2*)(HBsrc + o); hv = (f32x4){bflo(hw.x), bfhi(hw.x), bflo(hw.y), bfhi(hw.y)}; } else hv = *(const f32x4*)(H + o);
;                         const f32x4 v = hv + acc[ai][bj][m][n];
;                         *(f32x4*)(H + o) = v; ss += (v[0] * v[0] + v[1] * v[1]) + (v[2] * v[2] + v[3] * v[3]);
;                     }
;                 if (sh2) { ss += __shfl_xor(ss, 16); ss += __shfl_xor(ss, 32); if (fq == 0) atomicAdd(sh2 + row, ss); }
.LBB0_1876:
	s_or_b64 exec, exec, s[6:7]
	v_add_u32_e32 v34, 0xa0, v132
	s_waitcnt lgkmcnt(0)
	v_ashrrev_i32_e32 v35, 31, v34
	v_lshlrev_b64 v[36:37], 10, v[34:35]
	v_lshl_add_u64 v[36:37], v[36:37], 0, v[134:135]
	v_lshl_add_u64 v[40:41], v[36:37], 2, s[8:9]
	global_load_dwordx4 v[150:153], v[40:41], off
	global_load_dwordx4 v[154:157], v[40:41], off offset:64
	global_load_dwordx4 v[158:161], v[40:41], off offset:512
	global_load_dwordx4 v[162:165], v[40:41], off offset:576
	s_waitcnt vmcnt(3)
	s_nop 0
	v_mov_b32_e32 v36, v150
	v_mov_b32_e32 v37, v151
	v_mov_b32_e32 v38, v152
	v_mov_b32_e32 v39, v153
	v_pk_add_f32 v[32:33], v[32:33], v[38:39]
	v_pk_add_f32 v[30:31], v[30:31], v[36:37]
	global_store_dwordx4 v[40:41], v[30:33], off
	s_nop 1
	v_mul_f32_e32 v31, v31, v31
	v_fmac_f32_e32 v31, v30, v30
	v_mul_f32_e32 v30, v33, v33
	v_fmac_f32_e32 v30, v32, v32
	v_add_f32_e32 v36, v31, v30
	s_waitcnt vmcnt(3)
	s_nop 0
	v_mov_b32_e32 v30, v154
	v_mov_b32_e32 v31, v155
	v_mov_b32_e32 v32, v156
	v_mov_b32_e32 v33, v157
	v_pk_add_f32 v[28:29], v[28:29], v[32:33]
	v_pk_add_f32 v[26:27], v[26:27], v[30:31]
	global_store_dwordx4 v[40:41], v[26:29], off offset:64
	s_nop 1
	v_mul_f32_e32 v27, v27, v27
	v_fmac_f32_e32 v27, v26, v26
	v_mul_f32_e32 v26, v29, v29
	v_fmac_f32_e32 v26, v28, v28
	v_add_f32_e32 v26, v27, v26
	v_add_f32_e32 v30, v36, v26
	s_waitcnt vmcnt(3)
	s_nop 0
	v_mov_b32_e32 v26, v158
	v_mov_b32_e32 v27, v159
	v_mov_b32_e32 v28, v160
	v_mov_b32_e32 v29, v161
	v_pk_add_f32 v[24:25], v[24:25], v[28:29]
	v_pk_add_f32 v[22:23], v[22:23], v[26:27]
	global_store_dwordx4 v[40:41], v[22:25], off offset:512
	s_nop 1
	v_mul_f32_e32 v23, v23, v23
	v_fmac_f32_e32 v23, v22, v22
	v_mul_f32_e32 v22, v25, v25
	v_fmac_f32_e32 v22, v24, v24
	v_add_f32_e32 v22, v23, v22
	v_add_f32_e32 v26, v30, v22
	s_waitcnt vmcnt(3)
	s_nop 0
	v_mov_b32_e32 v22, v162
	v_mov_b32_e32 v23, v163
	v_mov_b32_e32 v24, v164
	v_mov_b32_e32 v25, v165
	v_pk_add_f32 v[20:21], v[20:21], v[24:25]
	v_pk_add_f32 v[18:19], v[18:19], v[22:23]
	global_store_dwordx4 v[40:41], v[18:21], off offset:576
	s_nop 1
	v_mul_f32_e32 v19, v19, v19
	v_fmac_f32_e32 v19, v18, v18
	v_mul_f32_e32 v18, v21, v21
	v_fmac_f32_e32 v18, v20, v20
	v_add_f32_e32 v18, v19, v18
	v_add_f32_e32 v18, v26, v18
	ds_bpermute_b32 v19, v116, v18
	s_waitcnt lgkmcnt(0)
	v_add_f32_e32 v18, v18, v19
	ds_bpermute_b32 v19, v117, v18
	s_and_saveexec_b64 s[6:7], vcc
	s_cbranch_execz .LBB0_1878
	s_waitcnt lgkmcnt(0)
	v_add_f32_e32 v20, v18, v19
	v_lshl_add_u64 v[18:19], v[34:35], 2, s[10:11]
	global_atomic_add_f32 v[18:19], v20, off
.LBB0_1878:
	s_or_b64 exec, exec, s[6:7]
	v_add_u32_e32 v18, 0xb0, v132
	s_waitcnt lgkmcnt(0)
	v_ashrrev_i32_e32 v19, 31, v18
	v_lshlrev_b64 v[20:21], 10, v[18:19]
	v_lshl_add_u64 v[20:21], v[20:21], 0, v[134:135]
	v_lshl_add_u64 v[24:25], v[20:21], 2, s[8:9]
	global_load_dwordx4 v[150:153], v[24:25], off
	global_load_dwordx4 v[154:157], v[24:25], off offset:64
	global_load_dwordx4 v[158:161], v[24:25], off offset:512
	global_load_dwordx4 v[162:165], v[24:25], off offset:576
	s_waitcnt vmcnt(3)
	s_nop 0
	v_mov_b32_e32 v20, v150
	v_mov_b32_e32 v21, v151
	v_mov_b32_e32 v22, v152
	v_mov_b32_e32 v23, v153
	v_pk_add_f32 v[16:17], v[16:17], v[22:23]
	v_pk_add_f32 v[14:15], v[14:15], v[20:21]
	global_store_dwordx4 v[24:25], v[14:17], off
	s_nop 1
	v_mul_f32_e32 v15, v15, v15
	v_fmac_f32_e32 v15, v14, v14
	v_mul_f32_e32 v14, v17, v17
	v_fmac_f32_e32 v14, v16, v16
	v_add_f32_e32 v20, v15, v14
	s_waitcnt vmcnt(3)
	s_nop 0
	v_mov_b32_e32 v14, v154
	v_mov_b32_e32 v15, v155
	v_mov_b32_e32 v16, v156
	v_mov_b32_e32 v17, v157
	v_pk_add_f32 v[12:13], v[12:13], v[16:17]
	v_pk_add_f32 v[10:11], v[10:11], v[14:15]
	global_store_dwordx4 v[24:25], v[10:13], off offset:64
	s_nop 1
	v_mul_f32_e32 v11, v11, v11
	v_fmac_f32_e32 v11, v10, v10
	v_mul_f32_e32 v10, v13, v13
	v_fmac_f32_e32 v10, v12, v12
	v_add_f32_e32 v10, v11, v10
	v_add_f32_e32 v14, v20, v10
	s_waitcnt vmcnt(3)
	s_nop 0
	v_mov_b32_e32 v10, v158
	v_mov_b32_e32 v11, v159
	v_mov_b32_e32 v12, v160
	v_mov_b32_e32 v13, v161
	v_pk_add_f32 v[8:9], v[8:9], v[12:13]
	v_pk_add_f32 v[6:7], v[6:7], v[10:11]
	global_store_dwordx4 v[24:25], v[6:9], off offset:512
	s_nop 1
	v_mul_f32_e32 v7, v7, v7
	v_fmac_f32_e32 v7, v6, v6
	v_mul_f32_e32 v6, v9, v9
	v_fmac_f32_e32 v6, v8, v8
	v_add_f32_e32 v6, v7, v6
	v_add_f32_e32 v10, v14, v6
	s_waitcnt vmcnt(3)
	s_nop 0
	v_mov_b32_e32 v6, v162
	v_mov_b32_e32 v7, v163
	v_mov_b32_e32 v8, v164
	v_mov_b32_e32 v9, v165
	v_pk_add_f32 v[4:5], v[4:5], v[8:9]
	v_pk_add_f32 v[2:3], v[2:3], v[6:7]
	global_store_dwordx4 v[24:25], v[2:5], off offset:576
	s_nop 1
	v_mul_f32_e32 v3, v3, v3
	v_fmac_f32_e32 v3, v2, v2
	v_mul_f32_e32 v2, v5, v5
	v_fmac_f32_e32 v2, v4, v4
	v_add_f32_e32 v2, v3, v2
	v_add_f32_e32 v2, v10, v2
	ds_bpermute_b32 v3, v116, v2
	s_waitcnt lgkmcnt(0)
	v_add_f32_e32 v2, v2, v3
	ds_bpermute_b32 v3, v117, v2
	s_and_saveexec_b64 s[6:7], vcc
	s_cbranch_execz .LBB0_1855
	s_waitcnt lgkmcnt(0)
	v_add_f32_e32 v4, v2, v3
	v_lshl_add_u64 v[2:3], v[18:19], 2, s[10:11]
	global_atomic_add_f32 v[2:3], v4, off
	s_branch .LBB0_1855
